# attention gather loads without the sc0 cache hint
# baseline (speedup 1.0000x reference)
; #define LAS __attribute__((address_space(3)))
; __device__ __forceinline__ float bf_lo(unsigned v) { return __uint_as_float(v << 16); }
; __device__ __forceinline__ float bf_hi(unsigned v) { return __uint_as_float(v & 0xffff0000u); }
; __device__ __forceinline__ int lane_id() { int l; asm volatile("v_mbcnt_lo_u32_b32 %0, -1, 0\n\tv_mbcnt_hi_u32_b32 %0, -1, %0\n\ts_nop 1" : "=v"(l)); return l; }
; __device__ __forceinline__ void attn_query8(const unsigned char* __restrict__ KV8, const bf16_t* __restrict__ Z, const int* __restrict__ SEL, bf16_t* __restrict__ YMIX, int t, LAS float* sbuf  ) {
;     const int lane = lane_id(), hd = lane >> 3;
;     const int nsel = (t + 1 < 256) ? (t + 1) : 256, nb = (nsel + 7) >> 3;
;     int iv[4];
; #pragma unroll
;     for (int jj = 0; jj < 4; ++jj) { const int e = lane + 64 * jj; iv[jj] = (e < nsel) ? SEL[(size_t)t * 256 + e] : 0; }
;     f32x2v qf[8];
;     { const u32x4* qp = (const u32x4*)(Z + (size_t)t * ZLD + OFF_Q + lane * 16); const u32x4 a = qp[0], b = qp[1];
;       qf[0] = (f32x2v){bf_lo(a.x), bf_hi(a.x)}; qf[1] = (f32x2v){bf_lo(a.y), bf_hi(a.y)}; qf[2] = (f32x2v){bf_lo(a.z), bf_hi(a.z)}; qf[3] = (f32x2v){bf_lo(a.w), bf_hi(a.w)};
;       qf[4] = (f32x2v){bf_lo(b.x), bf_hi(b.x)}; qf[5] = (f32x2v){bf_lo(b.y), bf_hi(b.y)}; qf[6] = (f32x2v){bf_lo(b.z), bf_hi(b.z)}; qf[7] = (f32x2v){bf_lo(b.w), bf_hi(b.w)}; }
;     const __amdgpu_buffer_rsrc_t rs = __builtin_amdgcn_make_buffer_rsrc((void*)KV8, 0, 0x7fffffff, 0x00020000);
;     const int lvo = lane * 16;
;     LAS float* srow = sbuf + hd * 256;
;     u32x4 A[8], B[8], C[8];
;     const int lb = nb - 1;
;     ...
;     kv8_issue(A, rs, lvo, 0, iv, 0);
;     kv8_issue(B, rs, lvo, 0, iv, CLAMPB(1));
.Latt_idx_1:
	s_mul_i32 s10, s80, 0x2a00
	s_mul_hi_i32 s11, s80, 0x2a00
	s_add_u32 s10, s42, s10
	s_addc_u32 s11, s43, s11
	global_load_dwordx4 v[244:247], v146, s[10:11] offset:2048
	global_load_dwordx4 v[230:233], v146, s[10:11] offset:2064
	s_waitcnt vmcnt(0)
	ds_write_b32 v148, v240 offset:0
	ds_write_b32 v148, v241 offset:32
	ds_write_b32 v148, v242 offset:64
	ds_write_b32 v148, v243 offset:96
	s_waitcnt lgkmcnt(0)
	ds_read_b128 v[150:153], v139 offset:0
	ds_read_b128 v[154:157], v139 offset:16
	ds_read_b128 v[158:161], v139 offset:32
	ds_read_b128 v[162:165], v139 offset:48
	ds_read_b128 v[166:169], v139 offset:64
	ds_read_b128 v[170:173], v139 offset:80
	ds_read_b128 v[174:177], v139 offset:96
	ds_read_b128 v[178:181], v139 offset:112
	s_waitcnt lgkmcnt(0)
	v_lshl_add_u32 v150, v150, 8, v138
	v_lshl_add_u32 v151, v151, 8, v138
	v_lshl_add_u32 v152, v152, 8, v138
	v_lshl_add_u32 v153, v153, 8, v138
	v_lshl_add_u32 v154, v154, 8, v138
	v_lshl_add_u32 v155, v155, 8, v138
	v_lshl_add_u32 v156, v156, 8, v138
	v_lshl_add_u32 v157, v157, 8, v138
	v_lshl_add_u32 v158, v158, 8, v138
	v_lshl_add_u32 v159, v159, 8, v138
	v_lshl_add_u32 v160, v160, 8, v138
	v_lshl_add_u32 v161, v161, 8, v138
	v_lshl_add_u32 v162, v162, 8, v138
	v_lshl_add_u32 v163, v163, 8, v138
	v_lshl_add_u32 v164, v164, 8, v138
	v_lshl_add_u32 v165, v165, 8, v138
	v_lshl_add_u32 v166, v166, 8, v138
	v_lshl_add_u32 v167, v167, 8, v138
	v_lshl_add_u32 v168, v168, 8, v138
	v_lshl_add_u32 v169, v169, 8, v138
	v_lshl_add_u32 v170, v170, 8, v138
	v_lshl_add_u32 v171, v171, 8, v138
	v_lshl_add_u32 v172, v172, 8, v138
	v_lshl_add_u32 v173, v173, 8, v138
	v_lshl_add_u32 v174, v174, 8, v138
	v_lshl_add_u32 v175, v175, 8, v138
	v_lshl_add_u32 v176, v176, 8, v138
	v_lshl_add_u32 v177, v177, 8, v138
	v_lshl_add_u32 v178, v178, 8, v138
	v_lshl_add_u32 v179, v179, 8, v138
	v_lshl_add_u32 v180, v180, 8, v138
	v_lshl_add_u32 v181, v181, 8, v138
	buffer_load_dwordx4 v[0:3], v150, s[16:19], s26 offen
	buffer_load_dwordx4 v[4:7], v151, s[16:19], s26 offen
	buffer_load_dwordx4 v[8:11], v152, s[16:19], s26 offen
	buffer_load_dwordx4 v[12:15], v153, s[16:19], s26 offen
	buffer_load_dwordx4 v[16:19], v154, s[16:19], s26 offen
	buffer_load_dwordx4 v[20:23], v155, s[16:19], s26 offen
	buffer_load_dwordx4 v[24:27], v156, s[16:19], s26 offen
	buffer_load_dwordx4 v[28:31], v157, s[16:19], s26 offen
	buffer_load_dwordx4 v[32:35], v158, s[16:19], s26 offen
	buffer_load_dwordx4 v[36:39], v159, s[16:19], s26 offen
	buffer_load_dwordx4 v[40:43], v160, s[16:19], s26 offen
	buffer_load_dwordx4 v[44:47], v161, s[16:19], s26 offen
	buffer_load_dwordx4 v[48:51], v162, s[16:19], s26 offen
	buffer_load_dwordx4 v[52:55], v163, s[16:19], s26 offen
	buffer_load_dwordx4 v[56:59], v164, s[16:19], s26 offen
	buffer_load_dwordx4 v[60:63], v165, s[16:19], s26 offen
	buffer_load_dwordx4 v[64:67], v166, s[16:19], s26 offen
	buffer_load_dwordx4 v[68:71], v167, s[16:19], s26 offen
	buffer_load_dwordx4 v[72:75], v168, s[16:19], s26 offen
	buffer_load_dwordx4 v[76:79], v169, s[16:19], s26 offen
	buffer_load_dwordx4 v[80:83], v170, s[16:19], s26 offen
	buffer_load_dwordx4 v[84:87], v171, s[16:19], s26 offen
	buffer_load_dwordx4 v[88:91], v172, s[16:19], s26 offen
	buffer_load_dwordx4 v[92:95], v173, s[16:19], s26 offen
	buffer_load_dwordx4 v[96:99], v174, s[16:19], s26 offen
	buffer_load_dwordx4 v[100:103], v175, s[16:19], s26 offen
	buffer_load_dwordx4 v[104:107], v176, s[16:19], s26 offen
	buffer_load_dwordx4 v[108:111], v177, s[16:19], s26 offen
	buffer_load_dwordx4 v[112:115], v178, s[16:19], s26 offen
	buffer_load_dwordx4 v[116:119], v179, s[16:19], s26 offen
	buffer_load_dwordx4 v[120:123], v180, s[16:19], s26 offen
	buffer_load_dwordx4 v[124:127], v181, s[16:19], s26 offen

; #define LAS __attribute__((address_space(3)))
; __device__ __forceinline__ float red8(float v) { v += dpp_f<0xB1>(v); v += dpp_f<0x4E>(v); v += dpp_f<0x141>(v); return v; }
; __device__ __forceinline__ void kv8_issue(u32x4 (&buf)[8], __amdgpu_buffer_rsrc_t rs, int voff  , int sbase  , const int (&iv)[4], int b) {
;     const int jj = b >> 3, l0 = (b & 7) * 8;
;     const int ivb = (jj == 0) ? iv[0] : (jj == 1) ? iv[1] : (jj == 2) ? iv[2] : iv[3];
; #pragma unroll
;     for (int u = 0; u < 8; ++u) { const int si = __builtin_amdgcn_readlane(ivb, l0 + u); buf[u] = __builtin_amdgcn_raw_buffer_load_b128(rs, voff, si * 2048 + sbase, KV8_AUX); }
; }
; __device__ __forceinline__ void kv8_qk(const u32x4 (&buf)[8], const f32x2v (&q2)[8], LAS float* srow, int b, int lane) {
; #pragma unroll
;     for (int u = 0; u < 8; ++u) {
;         const u32x4 k = buf[u];
;         f32x2v s0 = q2[0] * __builtin_amdgcn_cvt_pk_f32_fp8(k.x, false), s1 = q2[1] * __builtin_amdgcn_cvt_pk_f32_fp8(k.x, true);
;         s0 = __builtin_elementwise_fma(q2[2], __builtin_amdgcn_cvt_pk_f32_fp8(k.y, false), s0); s1 = __builtin_elementwise_fma(q2[3], __builtin_amdgcn_cvt_pk_f32_fp8(k.y, true), s1);
;         s0 = __builtin_elementwise_fma(q2[4], __builtin_amdgcn_cvt_pk_f32_fp8(k.z, false), s0); s1 = __builtin_elementwise_fma(q2[5], __builtin_amdgcn_cvt_pk_f32_fp8(k.z, true), s1);
;         s0 = __builtin_elementwise_fma(q2[6], __builtin_amdgcn_cvt_pk_f32_fp8(k.w, false), s0); s1 = __builtin_elementwise_fma(q2[7], __builtin_amdgcn_cvt_pk_f32_fp8(k.w, true), s1);
;         const f32x2v t = s0 + s1;
;         const float s = red8(t.x + t.y);
;         if ((lane & 7) == 0) srow[b * 8 + u] = s;
;     }
; }
.Latt_idx_2:
	s_mul_i32 s10, s6, 0x2a00
	s_mul_hi_i32 s11, s6, 0x2a00
	s_add_u32 s10, s42, s10
	s_addc_u32 s11, s43, s11
	global_load_dwordx4 v[244:247], v146, s[10:11] offset:2048
	global_load_dwordx4 v[230:233], v146, s[10:11] offset:2064
	s_waitcnt vmcnt(37)
	v_cvt_pk_f32_fp8_e32 v[214:215], v0
	v_cvt_pk_f32_fp8_sdwa v[216:217], v0 src0_sel:WORD_1
	v_pk_mul_f32 v[128:129], v[214:215], v[182:183]
	v_cvt_pk_f32_fp8_e32 v[218:219], v1
	s_nop 0
	v_pk_fma_f32 v[128:129], v[184:185], v[216:217], v[128:129]
	v_cvt_pk_f32_fp8_sdwa v[220:221], v1 src0_sel:WORD_1
	v_pk_fma_f32 v[128:129], v[186:187], v[218:219], v[128:129]
	v_cvt_pk_f32_fp8_e32 v[222:223], v2
	v_pk_fma_f32 v[128:129], v[188:189], v[220:221], v[128:129]
	v_cvt_pk_f32_fp8_sdwa v[224:225], v2 src0_sel:WORD_1
	s_nop 0
	v_pk_fma_f32 v[128:129], v[190:191], v[222:223], v[128:129]
	v_cvt_pk_f32_fp8_e32 v[226:227], v3
	v_pk_fma_f32 v[128:129], v[192:193], v[224:225], v[128:129]
	v_cvt_pk_f32_fp8_sdwa v[228:229], v3 src0_sel:WORD_1
	v_pk_fma_f32 v[128:129], v[194:195], v[226:227], v[128:129]
	v_pk_fma_f32 v[128:129], v[196:197], v[228:229], v[128:129]
	buffer_load_dwordx4 v[0:3], v150, s[16:19], s27 offen
	s_nop 0
	v_add_f32_e32 v132, v128, v129
	s_waitcnt vmcnt(37)
	v_cvt_pk_f32_fp8_e32 v[214:215], v4
	v_cvt_pk_f32_fp8_sdwa v[216:217], v4 src0_sel:WORD_1
	v_pk_mul_f32 v[128:129], v[214:215], v[182:183]
	v_cvt_pk_f32_fp8_e32 v[218:219], v5
	v_add_f32_dpp v132, v132, v132 quad_perm:[1,0,3,2] row_mask:0xf bank_mask:0xf
	v_pk_fma_f32 v[128:129], v[184:185], v[216:217], v[128:129]
	v_cvt_pk_f32_fp8_sdwa v[220:221], v5 src0_sel:WORD_1
	v_pk_fma_f32 v[128:129], v[186:187], v[218:219], v[128:129]
	v_cvt_pk_f32_fp8_e32 v[222:223], v6
	v_pk_fma_f32 v[128:129], v[188:189], v[220:221], v[128:129]
	v_cvt_pk_f32_fp8_sdwa v[224:225], v6 src0_sel:WORD_1
	v_add_f32_dpp v132, v132, v132 quad_perm:[2,3,0,1] row_mask:0xf bank_mask:0xf
	v_pk_fma_f32 v[128:129], v[190:191], v[222:223], v[128:129]
	v_cvt_pk_f32_fp8_e32 v[226:227], v7
	v_pk_fma_f32 v[128:129], v[192:193], v[224:225], v[128:129]
	v_cvt_pk_f32_fp8_sdwa v[228:229], v7 src0_sel:WORD_1
	v_pk_fma_f32 v[128:129], v[194:195], v[226:227], v[128:129]
	v_pk_fma_f32 v[128:129], v[196:197], v[228:229], v[128:129]
	buffer_load_dwordx4 v[4:7], v151, s[16:19], s27 offen
	v_add_f32_dpp v150, v132, v132 row_half_mirror row_mask:0xf bank_mask:0xf
	v_add_f32_e32 v133, v128, v129
	s_waitcnt vmcnt(37)
	v_cvt_pk_f32_fp8_e32 v[214:215], v8
	v_cvt_pk_f32_fp8_sdwa v[216:217], v8 src0_sel:WORD_1
	v_pk_mul_f32 v[128:129], v[214:215], v[182:183]
	v_cvt_pk_f32_fp8_e32 v[218:219], v9
	v_add_f32_dpp v133, v133, v133 quad_perm:[1,0,3,2] row_mask:0xf bank_mask:0xf
	v_pk_fma_f32 v[128:129], v[184:185], v[216:217], v[128:129]
	v_cvt_pk_f32_fp8_sdwa v[220:221], v9 src0_sel:WORD_1
	v_pk_fma_f32 v[128:129], v[186:187], v[218:219], v[128:129]
	v_cvt_pk_f32_fp8_e32 v[222:223], v10
	v_pk_fma_f32 v[128:129], v[188:189], v[220:221], v[128:129]
	v_cvt_pk_f32_fp8_sdwa v[224:225], v10 src0_sel:WORD_1
	v_add_f32_dpp v133, v133, v133 quad_perm:[2,3,0,1] row_mask:0xf bank_mask:0xf
	v_pk_fma_f32 v[128:129], v[190:191], v[222:223], v[128:129]
	v_cvt_pk_f32_fp8_e32 v[226:227], v11
	v_pk_fma_f32 v[128:129], v[192:193], v[224:225], v[128:129]
	v_cvt_pk_f32_fp8_sdwa v[228:229], v11 src0_sel:WORD_1
	v_pk_fma_f32 v[128:129], v[194:195], v[226:227], v[128:129]
	v_pk_fma_f32 v[128:129], v[196:197], v[228:229], v[128:129]
	buffer_load_dwordx4 v[8:11], v152, s[16:19], s27 offen
	v_add_f32_dpp v151, v133, v133 row_half_mirror row_mask:0xf bank_mask:0xf
	v_add_f32_e32 v132, v128, v129
	s_waitcnt vmcnt(37)
	v_cvt_pk_f32_fp8_e32 v[214:215], v12
	v_cvt_pk_f32_fp8_sdwa v[216:217], v12 src0_sel:WORD_1
	v_pk_mul_f32 v[128:129], v[214:215], v[182:183]
	v_cvt_pk_f32_fp8_e32 v[218:219], v13
	v_add_f32_dpp v132, v132, v132 quad_perm:[1,0,3,2] row_mask:0xf bank_mask:0xf
	v_pk_fma_f32 v[128:129], v[184:185], v[216:217], v[128:129]
	v_cvt_pk_f32_fp8_sdwa v[220:221], v13 src0_sel:WORD_1
	v_pk_fma_f32 v[128:129], v[186:187], v[218:219], v[128:129]
	v_cvt_pk_f32_fp8_e32 v[222:223], v14
	v_pk_fma_f32 v[128:129], v[188:189], v[220:221], v[128:129]
	v_cvt_pk_f32_fp8_sdwa v[224:225], v14 src0_sel:WORD_1
	v_add_f32_dpp v132, v132, v132 quad_perm:[2,3,0,1] row_mask:0xf bank_mask:0xf
	v_pk_fma_f32 v[128:129], v[190:191], v[222:223], v[128:129]
	v_cvt_pk_f32_fp8_e32 v[226:227], v15
	v_pk_fma_f32 v[128:129], v[192:193], v[224:225], v[128:129]
	v_cvt_pk_f32_fp8_sdwa v[228:229], v15 src0_sel:WORD_1
	v_pk_fma_f32 v[128:129], v[194:195], v[226:227], v[128:129]
	v_pk_fma_f32 v[128:129], v[196:197], v[228:229], v[128:129]
	buffer_load_dwordx4 v[12:15], v153, s[16:19], s27 offen
	v_add_f32_dpp v152, v132, v132 row_half_mirror row_mask:0xf bank_mask:0xf
	v_add_f32_e32 v133, v128, v129
	s_waitcnt vmcnt(37)
	v_cvt_pk_f32_fp8_e32 v[214:215], v16
	v_cvt_pk_f32_fp8_sdwa v[216:217], v16 src0_sel:WORD_1
	v_pk_mul_f32 v[128:129], v[214:215], v[182:183]
	v_cvt_pk_f32_fp8_e32 v[218:219], v17
	v_add_f32_dpp v133, v133, v133 quad_perm:[1,0,3,2] row_mask:0xf bank_mask:0xf
	v_pk_fma_f32 v[128:129], v[184:185], v[216:217], v[128:129]
	v_cvt_pk_f32_fp8_sdwa v[220:221], v17 src0_sel:WORD_1
	v_pk_fma_f32 v[128:129], v[186:187], v[218:219], v[128:129]
	v_cvt_pk_f32_fp8_e32 v[222:223], v18
	v_pk_fma_f32 v[128:129], v[188:189], v[220:221], v[128:129]
	v_cvt_pk_f32_fp8_sdwa v[224:225], v18 src0_sel:WORD_1
	v_add_f32_dpp v133, v133, v133 quad_perm:[2,3,0,1] row_mask:0xf bank_mask:0xf
	v_pk_fma_f32 v[128:129], v[190:191], v[222:223], v[128:129]
	v_cvt_pk_f32_fp8_e32 v[226:227], v19
	v_pk_fma_f32 v[128:129], v[192:193], v[224:225], v[128:129]
	v_cvt_pk_f32_fp8_sdwa v[228:229], v19 src0_sel:WORD_1
	v_pk_fma_f32 v[128:129], v[194:195], v[226:227], v[128:129]
	v_pk_fma_f32 v[128:129], v[196:197], v[228:229], v[128:129]
	buffer_load_dwordx4 v[16:19], v154, s[16:19], s27 offen
	v_add_f32_dpp v153, v133, v133 row_half_mirror row_mask:0xf bank_mask:0xf
	v_add_f32_e32 v132, v128, v129
	s_waitcnt vmcnt(37)
; #define LAS __attribute__((address_space(3)))
; __device__ __forceinline__ float red8(float v) { v += dpp_f<0xB1>(v); v += dpp_f<0x4E>(v); v += dpp_f<0x141>(v); return v; }
; __device__ __forceinline__ void kv8_issue(u32x4 (&buf)[8], __amdgpu_buffer_rsrc_t rs, int voff  , int sbase  , const int (&iv)[4], int b) {
;     const int jj = b >> 3, l0 = (b & 7) * 8;
;     const int ivb = (jj == 0) ? iv[0] : (jj == 1) ? iv[1] : (jj == 2) ? iv[2] : iv[3];
; #pragma unroll
;     for (int u = 0; u < 8; ++u) { const int si = __builtin_amdgcn_readlane(ivb, l0 + u); buf[u] = __builtin_amdgcn_raw_buffer_load_b128(rs, voff, si * 2048 + sbase, KV8_AUX); }
; }
; __device__ __forceinline__ void kv8_qk(const u32x4 (&buf)[8], const f32x2v (&q2)[8], LAS float* srow, int b, int lane) {
; #pragma unroll
;     for (int u = 0; u < 8; ++u) {
;         const u32x4 k = buf[u];
;         f32x2v s0 = q2[0] * __builtin_amdgcn_cvt_pk_f32_fp8(k.x, false), s1 = q2[1] * __builtin_amdgcn_cvt_pk_f32_fp8(k.x, true);
;         s0 = __builtin_elementwise_fma(q2[2], __builtin_amdgcn_cvt_pk_f32_fp8(k.y, false), s0); s1 = __builtin_elementwise_fma(q2[3], __builtin_amdgcn_cvt_pk_f32_fp8(k.y, true), s1);
;         s0 = __builtin_elementwise_fma(q2[4], __builtin_amdgcn_cvt_pk_f32_fp8(k.z, false), s0); s1 = __builtin_elementwise_fma(q2[5], __builtin_amdgcn_cvt_pk_f32_fp8(k.z, true), s1);
;         s0 = __builtin_elementwise_fma(q2[6], __builtin_amdgcn_cvt_pk_f32_fp8(k.w, false), s0); s1 = __builtin_elementwise_fma(q2[7], __builtin_amdgcn_cvt_pk_f32_fp8(k.w, true), s1);
;         const f32x2v t = s0 + s1;
;         const float s = red8(t.x + t.y);
;         if ((lane & 7) == 0) srow[b * 8 + u] = s;
;     }
; }
	v_cvt_pk_f32_fp8_e32 v[214:215], v20
	v_cvt_pk_f32_fp8_sdwa v[216:217], v20 src0_sel:WORD_1
	v_pk_mul_f32 v[128:129], v[214:215], v[182:183]
	v_cvt_pk_f32_fp8_e32 v[218:219], v21
	v_add_f32_dpp v132, v132, v132 quad_perm:[1,0,3,2] row_mask:0xf bank_mask:0xf
	v_pk_fma_f32 v[128:129], v[184:185], v[216:217], v[128:129]
	v_cvt_pk_f32_fp8_sdwa v[220:221], v21 src0_sel:WORD_1
	v_pk_fma_f32 v[128:129], v[186:187], v[218:219], v[128:129]
	v_cvt_pk_f32_fp8_e32 v[222:223], v22
	v_pk_fma_f32 v[128:129], v[188:189], v[220:221], v[128:129]
	v_cvt_pk_f32_fp8_sdwa v[224:225], v22 src0_sel:WORD_1
	v_add_f32_dpp v132, v132, v132 quad_perm:[2,3,0,1] row_mask:0xf bank_mask:0xf
	v_pk_fma_f32 v[128:129], v[190:191], v[222:223], v[128:129]
	v_cvt_pk_f32_fp8_e32 v[226:227], v23
	v_pk_fma_f32 v[128:129], v[192:193], v[224:225], v[128:129]
	v_cvt_pk_f32_fp8_sdwa v[228:229], v23 src0_sel:WORD_1
	v_pk_fma_f32 v[128:129], v[194:195], v[226:227], v[128:129]
	v_pk_fma_f32 v[128:129], v[196:197], v[228:229], v[128:129]
	buffer_load_dwordx4 v[20:23], v155, s[16:19], s27 offen
	v_add_f32_dpp v154, v132, v132 row_half_mirror row_mask:0xf bank_mask:0xf
	v_add_f32_e32 v133, v128, v129
	s_waitcnt vmcnt(37)
	v_cvt_pk_f32_fp8_e32 v[214:215], v24
	v_cvt_pk_f32_fp8_sdwa v[216:217], v24 src0_sel:WORD_1
	v_pk_mul_f32 v[128:129], v[214:215], v[182:183]
	v_cvt_pk_f32_fp8_e32 v[218:219], v25
	v_add_f32_dpp v133, v133, v133 quad_perm:[1,0,3,2] row_mask:0xf bank_mask:0xf
	v_pk_fma_f32 v[128:129], v[184:185], v[216:217], v[128:129]
	v_cvt_pk_f32_fp8_sdwa v[220:221], v25 src0_sel:WORD_1
	v_pk_fma_f32 v[128:129], v[186:187], v[218:219], v[128:129]
	v_cvt_pk_f32_fp8_e32 v[222:223], v26
	v_pk_fma_f32 v[128:129], v[188:189], v[220:221], v[128:129]
	v_cvt_pk_f32_fp8_sdwa v[224:225], v26 src0_sel:WORD_1
	v_add_f32_dpp v133, v133, v133 quad_perm:[2,3,0,1] row_mask:0xf bank_mask:0xf
	v_pk_fma_f32 v[128:129], v[190:191], v[222:223], v[128:129]
	v_cvt_pk_f32_fp8_e32 v[226:227], v27
	v_pk_fma_f32 v[128:129], v[192:193], v[224:225], v[128:129]
	v_cvt_pk_f32_fp8_sdwa v[228:229], v27 src0_sel:WORD_1
	v_pk_fma_f32 v[128:129], v[194:195], v[226:227], v[128:129]
	v_pk_fma_f32 v[128:129], v[196:197], v[228:229], v[128:129]
	buffer_load_dwordx4 v[24:27], v156, s[16:19], s27 offen
	v_add_f32_dpp v155, v133, v133 row_half_mirror row_mask:0xf bank_mask:0xf
	v_add_f32_e32 v132, v128, v129
	s_waitcnt vmcnt(37)
	v_cvt_pk_f32_fp8_e32 v[214:215], v28
	v_cvt_pk_f32_fp8_sdwa v[216:217], v28 src0_sel:WORD_1
	v_pk_mul_f32 v[128:129], v[214:215], v[182:183]
	v_cvt_pk_f32_fp8_e32 v[218:219], v29
	v_add_f32_dpp v132, v132, v132 quad_perm:[1,0,3,2] row_mask:0xf bank_mask:0xf
	v_pk_fma_f32 v[128:129], v[184:185], v[216:217], v[128:129]
	v_cvt_pk_f32_fp8_sdwa v[220:221], v29 src0_sel:WORD_1
	v_pk_fma_f32 v[128:129], v[186:187], v[218:219], v[128:129]
	v_cvt_pk_f32_fp8_e32 v[222:223], v30
	v_pk_fma_f32 v[128:129], v[188:189], v[220:221], v[128:129]
	v_cvt_pk_f32_fp8_sdwa v[224:225], v30 src0_sel:WORD_1
	v_add_f32_dpp v132, v132, v132 quad_perm:[2,3,0,1] row_mask:0xf bank_mask:0xf
	v_pk_fma_f32 v[128:129], v[190:191], v[222:223], v[128:129]
	v_cvt_pk_f32_fp8_e32 v[226:227], v31
	v_pk_fma_f32 v[128:129], v[192:193], v[224:225], v[128:129]
	v_cvt_pk_f32_fp8_sdwa v[228:229], v31 src0_sel:WORD_1
	v_pk_fma_f32 v[128:129], v[194:195], v[226:227], v[128:129]
	v_pk_fma_f32 v[128:129], v[196:197], v[228:229], v[128:129]
	buffer_load_dwordx4 v[28:31], v157, s[16:19], s27 offen
	v_add_f32_dpp v156, v132, v132 row_half_mirror row_mask:0xf bank_mask:0xf
	v_add_f32_e32 v133, v128, v129
	s_waitcnt vmcnt(37)
	v_cvt_pk_f32_fp8_e32 v[214:215], v32
	v_cvt_pk_f32_fp8_sdwa v[216:217], v32 src0_sel:WORD_1
	v_pk_mul_f32 v[128:129], v[214:215], v[182:183]
	v_cvt_pk_f32_fp8_e32 v[218:219], v33
	v_add_f32_dpp v133, v133, v133 quad_perm:[1,0,3,2] row_mask:0xf bank_mask:0xf
	v_pk_fma_f32 v[128:129], v[184:185], v[216:217], v[128:129]
	v_cvt_pk_f32_fp8_sdwa v[220:221], v33 src0_sel:WORD_1
	v_pk_fma_f32 v[128:129], v[186:187], v[218:219], v[128:129]
	v_cvt_pk_f32_fp8_e32 v[222:223], v34
	v_pk_fma_f32 v[128:129], v[188:189], v[220:221], v[128:129]
	v_cvt_pk_f32_fp8_sdwa v[224:225], v34 src0_sel:WORD_1
	v_add_f32_dpp v133, v133, v133 quad_perm:[2,3,0,1] row_mask:0xf bank_mask:0xf
	v_pk_fma_f32 v[128:129], v[190:191], v[222:223], v[128:129]
	v_cvt_pk_f32_fp8_e32 v[226:227], v35
	v_pk_fma_f32 v[128:129], v[192:193], v[224:225], v[128:129]
	v_cvt_pk_f32_fp8_sdwa v[228:229], v35 src0_sel:WORD_1
	v_pk_fma_f32 v[128:129], v[194:195], v[226:227], v[128:129]
	v_pk_fma_f32 v[128:129], v[196:197], v[228:229], v[128:129]
	buffer_load_dwordx4 v[32:35], v158, s[16:19], s27 offen
	v_add_f32_dpp v157, v133, v133 row_half_mirror row_mask:0xf bank_mask:0xf
	v_add_f32_e32 v132, v128, v129
	s_waitcnt vmcnt(37)
	v_cvt_pk_f32_fp8_e32 v[214:215], v36
	v_cvt_pk_f32_fp8_sdwa v[216:217], v36 src0_sel:WORD_1
	v_pk_mul_f32 v[128:129], v[214:215], v[182:183]
	v_cvt_pk_f32_fp8_e32 v[218:219], v37
	v_add_f32_dpp v132, v132, v132 quad_perm:[1,0,3,2] row_mask:0xf bank_mask:0xf
	v_pk_fma_f32 v[128:129], v[184:185], v[216:217], v[128:129]
	v_cvt_pk_f32_fp8_sdwa v[220:221], v37 src0_sel:WORD_1
	v_pk_fma_f32 v[128:129], v[186:187], v[218:219], v[128:129]
	v_cvt_pk_f32_fp8_e32 v[222:223], v38
	v_pk_fma_f32 v[128:129], v[188:189], v[220:221], v[128:129]
	v_cvt_pk_f32_fp8_sdwa v[224:225], v38 src0_sel:WORD_1
	v_add_f32_dpp v132, v132, v132 quad_perm:[2,3,0,1] row_mask:0xf bank_mask:0xf
	v_pk_fma_f32 v[128:129], v[190:191], v[222:223], v[128:129]
	v_cvt_pk_f32_fp8_e32 v[226:227], v39
	v_pk_fma_f32 v[128:129], v[192:193], v[224:225], v[128:129]
	v_cvt_pk_f32_fp8_sdwa v[228:229], v39 src0_sel:WORD_1
	v_pk_fma_f32 v[128:129], v[194:195], v[226:227], v[128:129]
	v_pk_fma_f32 v[128:129], v[196:197], v[228:229], v[128:129]
	buffer_load_dwordx4 v[36:39], v159, s[16:19], s27 offen
	v_add_f32_dpp v158, v132, v132 row_half_mirror row_mask:0xf bank_mask:0xf
	v_add_f32_e32 v133, v128, v129
	s_waitcnt vmcnt(37)
; #define LAS __attribute__((address_space(3)))
; __device__ __forceinline__ float red8(float v) { v += dpp_f<0xB1>(v); v += dpp_f<0x4E>(v); v += dpp_f<0x141>(v); return v; }
; __device__ __forceinline__ void kv8_issue(u32x4 (&buf)[8], __amdgpu_buffer_rsrc_t rs, int voff  , int sbase  , const int (&iv)[4], int b) {
;     const int jj = b >> 3, l0 = (b & 7) * 8;
;     const int ivb = (jj == 0) ? iv[0] : (jj == 1) ? iv[1] : (jj == 2) ? iv[2] : iv[3];
; #pragma unroll
;     for (int u = 0; u < 8; ++u) { const int si = __builtin_amdgcn_readlane(ivb, l0 + u); buf[u] = __builtin_amdgcn_raw_buffer_load_b128(rs, voff, si * 2048 + sbase, KV8_AUX); }
; }
; __device__ __forceinline__ void kv8_qk(const u32x4 (&buf)[8], const f32x2v (&q2)[8], LAS float* srow, int b, int lane) {
; #pragma unroll
;     for (int u = 0; u < 8; ++u) {
;         const u32x4 k = buf[u];
;         f32x2v s0 = q2[0] * __builtin_amdgcn_cvt_pk_f32_fp8(k.x, false), s1 = q2[1] * __builtin_amdgcn_cvt_pk_f32_fp8(k.x, true);
;         s0 = __builtin_elementwise_fma(q2[2], __builtin_amdgcn_cvt_pk_f32_fp8(k.y, false), s0); s1 = __builtin_elementwise_fma(q2[3], __builtin_amdgcn_cvt_pk_f32_fp8(k.y, true), s1);
;         s0 = __builtin_elementwise_fma(q2[4], __builtin_amdgcn_cvt_pk_f32_fp8(k.z, false), s0); s1 = __builtin_elementwise_fma(q2[5], __builtin_amdgcn_cvt_pk_f32_fp8(k.z, true), s1);
;         s0 = __builtin_elementwise_fma(q2[6], __builtin_amdgcn_cvt_pk_f32_fp8(k.w, false), s0); s1 = __builtin_elementwise_fma(q2[7], __builtin_amdgcn_cvt_pk_f32_fp8(k.w, true), s1);
;         const f32x2v t = s0 + s1;
;         const float s = red8(t.x + t.y);
;         if ((lane & 7) == 0) srow[b * 8 + u] = s;
;     }
; }
	v_cvt_pk_f32_fp8_e32 v[214:215], v40
	v_cvt_pk_f32_fp8_sdwa v[216:217], v40 src0_sel:WORD_1
	v_pk_mul_f32 v[128:129], v[214:215], v[182:183]
	v_cvt_pk_f32_fp8_e32 v[218:219], v41
	v_add_f32_dpp v133, v133, v133 quad_perm:[1,0,3,2] row_mask:0xf bank_mask:0xf
	v_pk_fma_f32 v[128:129], v[184:185], v[216:217], v[128:129]
	v_cvt_pk_f32_fp8_sdwa v[220:221], v41 src0_sel:WORD_1
	v_pk_fma_f32 v[128:129], v[186:187], v[218:219], v[128:129]
	v_cvt_pk_f32_fp8_e32 v[222:223], v42
	v_pk_fma_f32 v[128:129], v[188:189], v[220:221], v[128:129]
	v_cvt_pk_f32_fp8_sdwa v[224:225], v42 src0_sel:WORD_1
	v_add_f32_dpp v133, v133, v133 quad_perm:[2,3,0,1] row_mask:0xf bank_mask:0xf
	v_pk_fma_f32 v[128:129], v[190:191], v[222:223], v[128:129]
	v_cvt_pk_f32_fp8_e32 v[226:227], v43
	v_pk_fma_f32 v[128:129], v[192:193], v[224:225], v[128:129]
	v_cvt_pk_f32_fp8_sdwa v[228:229], v43 src0_sel:WORD_1
	v_pk_fma_f32 v[128:129], v[194:195], v[226:227], v[128:129]
	v_pk_fma_f32 v[128:129], v[196:197], v[228:229], v[128:129]
	buffer_load_dwordx4 v[40:43], v160, s[16:19], s27 offen
	v_add_f32_dpp v159, v133, v133 row_half_mirror row_mask:0xf bank_mask:0xf
	v_add_f32_e32 v132, v128, v129
	s_waitcnt vmcnt(37)
	v_cvt_pk_f32_fp8_e32 v[214:215], v44
	v_cvt_pk_f32_fp8_sdwa v[216:217], v44 src0_sel:WORD_1
	v_pk_mul_f32 v[128:129], v[214:215], v[182:183]
	v_cvt_pk_f32_fp8_e32 v[218:219], v45
	v_add_f32_dpp v132, v132, v132 quad_perm:[1,0,3,2] row_mask:0xf bank_mask:0xf
	v_pk_fma_f32 v[128:129], v[184:185], v[216:217], v[128:129]
	v_cvt_pk_f32_fp8_sdwa v[220:221], v45 src0_sel:WORD_1
	v_pk_fma_f32 v[128:129], v[186:187], v[218:219], v[128:129]
	v_cvt_pk_f32_fp8_e32 v[222:223], v46
	v_pk_fma_f32 v[128:129], v[188:189], v[220:221], v[128:129]
	v_cvt_pk_f32_fp8_sdwa v[224:225], v46 src0_sel:WORD_1
	v_add_f32_dpp v132, v132, v132 quad_perm:[2,3,0,1] row_mask:0xf bank_mask:0xf
	v_pk_fma_f32 v[128:129], v[190:191], v[222:223], v[128:129]
	v_cvt_pk_f32_fp8_e32 v[226:227], v47
	v_pk_fma_f32 v[128:129], v[192:193], v[224:225], v[128:129]
	v_cvt_pk_f32_fp8_sdwa v[228:229], v47 src0_sel:WORD_1
	v_pk_fma_f32 v[128:129], v[194:195], v[226:227], v[128:129]
	v_pk_fma_f32 v[128:129], v[196:197], v[228:229], v[128:129]
	buffer_load_dwordx4 v[44:47], v161, s[16:19], s27 offen
	v_add_f32_dpp v160, v132, v132 row_half_mirror row_mask:0xf bank_mask:0xf
	v_add_f32_e32 v133, v128, v129
	s_waitcnt vmcnt(37)
	v_cvt_pk_f32_fp8_e32 v[214:215], v48
	v_cvt_pk_f32_fp8_sdwa v[216:217], v48 src0_sel:WORD_1
	v_pk_mul_f32 v[128:129], v[214:215], v[182:183]
	v_cvt_pk_f32_fp8_e32 v[218:219], v49
	v_add_f32_dpp v133, v133, v133 quad_perm:[1,0,3,2] row_mask:0xf bank_mask:0xf
	v_pk_fma_f32 v[128:129], v[184:185], v[216:217], v[128:129]
	v_cvt_pk_f32_fp8_sdwa v[220:221], v49 src0_sel:WORD_1
	v_pk_fma_f32 v[128:129], v[186:187], v[218:219], v[128:129]
	v_cvt_pk_f32_fp8_e32 v[222:223], v50
	v_pk_fma_f32 v[128:129], v[188:189], v[220:221], v[128:129]
	v_cvt_pk_f32_fp8_sdwa v[224:225], v50 src0_sel:WORD_1
	v_add_f32_dpp v133, v133, v133 quad_perm:[2,3,0,1] row_mask:0xf bank_mask:0xf
	v_pk_fma_f32 v[128:129], v[190:191], v[222:223], v[128:129]
	v_cvt_pk_f32_fp8_e32 v[226:227], v51
	v_pk_fma_f32 v[128:129], v[192:193], v[224:225], v[128:129]
	v_cvt_pk_f32_fp8_sdwa v[228:229], v51 src0_sel:WORD_1
	v_pk_fma_f32 v[128:129], v[194:195], v[226:227], v[128:129]
	v_pk_fma_f32 v[128:129], v[196:197], v[228:229], v[128:129]
	buffer_load_dwordx4 v[48:51], v162, s[16:19], s27 offen
	v_add_f32_dpp v161, v133, v133 row_half_mirror row_mask:0xf bank_mask:0xf
	v_add_f32_e32 v132, v128, v129
	s_waitcnt vmcnt(37)
	v_cvt_pk_f32_fp8_e32 v[214:215], v52
	v_cvt_pk_f32_fp8_sdwa v[216:217], v52 src0_sel:WORD_1
	v_pk_mul_f32 v[128:129], v[214:215], v[182:183]
	v_cvt_pk_f32_fp8_e32 v[218:219], v53
	v_add_f32_dpp v132, v132, v132 quad_perm:[1,0,3,2] row_mask:0xf bank_mask:0xf
	v_pk_fma_f32 v[128:129], v[184:185], v[216:217], v[128:129]
	v_cvt_pk_f32_fp8_sdwa v[220:221], v53 src0_sel:WORD_1
	v_pk_fma_f32 v[128:129], v[186:187], v[218:219], v[128:129]
	v_cvt_pk_f32_fp8_e32 v[222:223], v54
	v_pk_fma_f32 v[128:129], v[188:189], v[220:221], v[128:129]
	v_cvt_pk_f32_fp8_sdwa v[224:225], v54 src0_sel:WORD_1
	v_add_f32_dpp v132, v132, v132 quad_perm:[2,3,0,1] row_mask:0xf bank_mask:0xf
	v_pk_fma_f32 v[128:129], v[190:191], v[222:223], v[128:129]
	v_cvt_pk_f32_fp8_e32 v[226:227], v55
	v_pk_fma_f32 v[128:129], v[192:193], v[224:225], v[128:129]
	v_cvt_pk_f32_fp8_sdwa v[228:229], v55 src0_sel:WORD_1
	v_pk_fma_f32 v[128:129], v[194:195], v[226:227], v[128:129]
	v_pk_fma_f32 v[128:129], v[196:197], v[228:229], v[128:129]
	buffer_load_dwordx4 v[52:55], v163, s[16:19], s27 offen
	v_add_f32_dpp v162, v132, v132 row_half_mirror row_mask:0xf bank_mask:0xf
	v_add_f32_e32 v133, v128, v129
	s_waitcnt vmcnt(37)
	v_cvt_pk_f32_fp8_e32 v[214:215], v56
	v_cvt_pk_f32_fp8_sdwa v[216:217], v56 src0_sel:WORD_1
	v_pk_mul_f32 v[128:129], v[214:215], v[182:183]
	v_cvt_pk_f32_fp8_e32 v[218:219], v57
	v_add_f32_dpp v133, v133, v133 quad_perm:[1,0,3,2] row_mask:0xf bank_mask:0xf
	v_pk_fma_f32 v[128:129], v[184:185], v[216:217], v[128:129]
	v_cvt_pk_f32_fp8_sdwa v[220:221], v57 src0_sel:WORD_1
	v_pk_fma_f32 v[128:129], v[186:187], v[218:219], v[128:129]
	v_cvt_pk_f32_fp8_e32 v[222:223], v58
	v_pk_fma_f32 v[128:129], v[188:189], v[220:221], v[128:129]
	v_cvt_pk_f32_fp8_sdwa v[224:225], v58 src0_sel:WORD_1
	v_add_f32_dpp v133, v133, v133 quad_perm:[2,3,0,1] row_mask:0xf bank_mask:0xf
	v_pk_fma_f32 v[128:129], v[190:191], v[222:223], v[128:129]
	v_cvt_pk_f32_fp8_e32 v[226:227], v59
	v_pk_fma_f32 v[128:129], v[192:193], v[224:225], v[128:129]
	v_cvt_pk_f32_fp8_sdwa v[228:229], v59 src0_sel:WORD_1
	v_pk_fma_f32 v[128:129], v[194:195], v[226:227], v[128:129]
	v_pk_fma_f32 v[128:129], v[196:197], v[228:229], v[128:129]
	buffer_load_dwordx4 v[56:59], v164, s[16:19], s27 offen
	v_add_f32_dpp v163, v133, v133 row_half_mirror row_mask:0xf bank_mask:0xf
	v_add_f32_e32 v132, v128, v129
	s_waitcnt vmcnt(37)
; #define LAS __attribute__((address_space(3)))
; __device__ __forceinline__ float red8(float v) { v += dpp_f<0xB1>(v); v += dpp_f<0x4E>(v); v += dpp_f<0x141>(v); return v; }
; __device__ __forceinline__ void kv8_issue(u32x4 (&buf)[8], __amdgpu_buffer_rsrc_t rs, int voff  , int sbase  , const int (&iv)[4], int b) {
;     const int jj = b >> 3, l0 = (b & 7) * 8;
;     const int ivb = (jj == 0) ? iv[0] : (jj == 1) ? iv[1] : (jj == 2) ? iv[2] : iv[3];
; #pragma unroll
;     for (int u = 0; u < 8; ++u) { const int si = __builtin_amdgcn_readlane(ivb, l0 + u); buf[u] = __builtin_amdgcn_raw_buffer_load_b128(rs, voff, si * 2048 + sbase, KV8_AUX); }
; }
; __device__ __forceinline__ void kv8_qk(const u32x4 (&buf)[8], const f32x2v (&q2)[8], LAS float* srow, int b, int lane) {
; #pragma unroll
;     for (int u = 0; u < 8; ++u) {
;         const u32x4 k = buf[u];
;         f32x2v s0 = q2[0] * __builtin_amdgcn_cvt_pk_f32_fp8(k.x, false), s1 = q2[1] * __builtin_amdgcn_cvt_pk_f32_fp8(k.x, true);
;         s0 = __builtin_elementwise_fma(q2[2], __builtin_amdgcn_cvt_pk_f32_fp8(k.y, false), s0); s1 = __builtin_elementwise_fma(q2[3], __builtin_amdgcn_cvt_pk_f32_fp8(k.y, true), s1);
;         s0 = __builtin_elementwise_fma(q2[4], __builtin_amdgcn_cvt_pk_f32_fp8(k.z, false), s0); s1 = __builtin_elementwise_fma(q2[5], __builtin_amdgcn_cvt_pk_f32_fp8(k.z, true), s1);
;         s0 = __builtin_elementwise_fma(q2[6], __builtin_amdgcn_cvt_pk_f32_fp8(k.w, false), s0); s1 = __builtin_elementwise_fma(q2[7], __builtin_amdgcn_cvt_pk_f32_fp8(k.w, true), s1);
;         const f32x2v t = s0 + s1;
;         const float s = red8(t.x + t.y);
;         if ((lane & 7) == 0) srow[b * 8 + u] = s;
;     }
; }
	v_cvt_pk_f32_fp8_e32 v[214:215], v60
	v_cvt_pk_f32_fp8_sdwa v[216:217], v60 src0_sel:WORD_1
	v_pk_mul_f32 v[128:129], v[214:215], v[182:183]
	v_cvt_pk_f32_fp8_e32 v[218:219], v61
	v_add_f32_dpp v132, v132, v132 quad_perm:[1,0,3,2] row_mask:0xf bank_mask:0xf
	v_pk_fma_f32 v[128:129], v[184:185], v[216:217], v[128:129]
	v_cvt_pk_f32_fp8_sdwa v[220:221], v61 src0_sel:WORD_1
	v_pk_fma_f32 v[128:129], v[186:187], v[218:219], v[128:129]
	v_cvt_pk_f32_fp8_e32 v[222:223], v62
	v_pk_fma_f32 v[128:129], v[188:189], v[220:221], v[128:129]
	v_cvt_pk_f32_fp8_sdwa v[224:225], v62 src0_sel:WORD_1
	v_add_f32_dpp v132, v132, v132 quad_perm:[2,3,0,1] row_mask:0xf bank_mask:0xf
	v_pk_fma_f32 v[128:129], v[190:191], v[222:223], v[128:129]
	v_cvt_pk_f32_fp8_e32 v[226:227], v63
	v_pk_fma_f32 v[128:129], v[192:193], v[224:225], v[128:129]
	v_cvt_pk_f32_fp8_sdwa v[228:229], v63 src0_sel:WORD_1
	v_pk_fma_f32 v[128:129], v[194:195], v[226:227], v[128:129]
	v_pk_fma_f32 v[128:129], v[196:197], v[228:229], v[128:129]
	buffer_load_dwordx4 v[60:63], v165, s[16:19], s27 offen
	v_add_f32_dpp v164, v132, v132 row_half_mirror row_mask:0xf bank_mask:0xf
	v_add_f32_e32 v133, v128, v129
	s_waitcnt vmcnt(37)
	v_cvt_pk_f32_fp8_e32 v[214:215], v64
	v_cvt_pk_f32_fp8_sdwa v[216:217], v64 src0_sel:WORD_1
	v_pk_mul_f32 v[128:129], v[214:215], v[182:183]
	v_cvt_pk_f32_fp8_e32 v[218:219], v65
	v_add_f32_dpp v133, v133, v133 quad_perm:[1,0,3,2] row_mask:0xf bank_mask:0xf
	v_pk_fma_f32 v[128:129], v[184:185], v[216:217], v[128:129]
	v_cvt_pk_f32_fp8_sdwa v[220:221], v65 src0_sel:WORD_1
	v_pk_fma_f32 v[128:129], v[186:187], v[218:219], v[128:129]
	v_cvt_pk_f32_fp8_e32 v[222:223], v66
	v_pk_fma_f32 v[128:129], v[188:189], v[220:221], v[128:129]
	v_cvt_pk_f32_fp8_sdwa v[224:225], v66 src0_sel:WORD_1
	v_add_f32_dpp v133, v133, v133 quad_perm:[2,3,0,1] row_mask:0xf bank_mask:0xf
	v_pk_fma_f32 v[128:129], v[190:191], v[222:223], v[128:129]
	v_cvt_pk_f32_fp8_e32 v[226:227], v67
	v_pk_fma_f32 v[128:129], v[192:193], v[224:225], v[128:129]
	v_cvt_pk_f32_fp8_sdwa v[228:229], v67 src0_sel:WORD_1
	v_pk_fma_f32 v[128:129], v[194:195], v[226:227], v[128:129]
	v_pk_fma_f32 v[128:129], v[196:197], v[228:229], v[128:129]
	buffer_load_dwordx4 v[64:67], v166, s[16:19], s27 offen
	v_add_f32_dpp v165, v133, v133 row_half_mirror row_mask:0xf bank_mask:0xf
	v_add_f32_e32 v132, v128, v129
	s_waitcnt vmcnt(37)
	v_cvt_pk_f32_fp8_e32 v[214:215], v68
	v_cvt_pk_f32_fp8_sdwa v[216:217], v68 src0_sel:WORD_1
	v_pk_mul_f32 v[128:129], v[214:215], v[182:183]
	v_cvt_pk_f32_fp8_e32 v[218:219], v69
	v_add_f32_dpp v132, v132, v132 quad_perm:[1,0,3,2] row_mask:0xf bank_mask:0xf
	v_pk_fma_f32 v[128:129], v[184:185], v[216:217], v[128:129]
	v_cvt_pk_f32_fp8_sdwa v[220:221], v69 src0_sel:WORD_1
	v_pk_fma_f32 v[128:129], v[186:187], v[218:219], v[128:129]
	v_cvt_pk_f32_fp8_e32 v[222:223], v70
	v_pk_fma_f32 v[128:129], v[188:189], v[220:221], v[128:129]
	v_cvt_pk_f32_fp8_sdwa v[224:225], v70 src0_sel:WORD_1
	v_add_f32_dpp v132, v132, v132 quad_perm:[2,3,0,1] row_mask:0xf bank_mask:0xf
	v_pk_fma_f32 v[128:129], v[190:191], v[222:223], v[128:129]
	v_cvt_pk_f32_fp8_e32 v[226:227], v71
	v_pk_fma_f32 v[128:129], v[192:193], v[224:225], v[128:129]
	v_cvt_pk_f32_fp8_sdwa v[228:229], v71 src0_sel:WORD_1
	v_pk_fma_f32 v[128:129], v[194:195], v[226:227], v[128:129]
	v_pk_fma_f32 v[128:129], v[196:197], v[228:229], v[128:129]
	buffer_load_dwordx4 v[68:71], v167, s[16:19], s27 offen
	v_add_f32_dpp v166, v132, v132 row_half_mirror row_mask:0xf bank_mask:0xf
	v_add_f32_e32 v133, v128, v129
	s_waitcnt vmcnt(37)
	v_cvt_pk_f32_fp8_e32 v[214:215], v72
	v_cvt_pk_f32_fp8_sdwa v[216:217], v72 src0_sel:WORD_1
	v_pk_mul_f32 v[128:129], v[214:215], v[182:183]
	v_cvt_pk_f32_fp8_e32 v[218:219], v73
	v_add_f32_dpp v133, v133, v133 quad_perm:[1,0,3,2] row_mask:0xf bank_mask:0xf
	v_pk_fma_f32 v[128:129], v[184:185], v[216:217], v[128:129]
	v_cvt_pk_f32_fp8_sdwa v[220:221], v73 src0_sel:WORD_1
	v_pk_fma_f32 v[128:129], v[186:187], v[218:219], v[128:129]
	v_cvt_pk_f32_fp8_e32 v[222:223], v74
	v_pk_fma_f32 v[128:129], v[188:189], v[220:221], v[128:129]
	v_cvt_pk_f32_fp8_sdwa v[224:225], v74 src0_sel:WORD_1
	v_add_f32_dpp v133, v133, v133 quad_perm:[2,3,0,1] row_mask:0xf bank_mask:0xf
	v_pk_fma_f32 v[128:129], v[190:191], v[222:223], v[128:129]
	v_cvt_pk_f32_fp8_e32 v[226:227], v75
	v_pk_fma_f32 v[128:129], v[192:193], v[224:225], v[128:129]
	v_cvt_pk_f32_fp8_sdwa v[228:229], v75 src0_sel:WORD_1
	v_pk_fma_f32 v[128:129], v[194:195], v[226:227], v[128:129]
	v_pk_fma_f32 v[128:129], v[196:197], v[228:229], v[128:129]
	buffer_load_dwordx4 v[72:75], v168, s[16:19], s27 offen
	v_add_f32_dpp v167, v133, v133 row_half_mirror row_mask:0xf bank_mask:0xf
	v_add_f32_e32 v132, v128, v129
	s_waitcnt vmcnt(37)
	v_cvt_pk_f32_fp8_e32 v[214:215], v76
	v_cvt_pk_f32_fp8_sdwa v[216:217], v76 src0_sel:WORD_1
	v_pk_mul_f32 v[128:129], v[214:215], v[182:183]
	v_cvt_pk_f32_fp8_e32 v[218:219], v77
	v_add_f32_dpp v132, v132, v132 quad_perm:[1,0,3,2] row_mask:0xf bank_mask:0xf
	v_pk_fma_f32 v[128:129], v[184:185], v[216:217], v[128:129]
	v_cvt_pk_f32_fp8_sdwa v[220:221], v77 src0_sel:WORD_1
	v_pk_fma_f32 v[128:129], v[186:187], v[218:219], v[128:129]
	v_cvt_pk_f32_fp8_e32 v[222:223], v78
	v_pk_fma_f32 v[128:129], v[188:189], v[220:221], v[128:129]
	v_cvt_pk_f32_fp8_sdwa v[224:225], v78 src0_sel:WORD_1
	v_add_f32_dpp v132, v132, v132 quad_perm:[2,3,0,1] row_mask:0xf bank_mask:0xf
	v_pk_fma_f32 v[128:129], v[190:191], v[222:223], v[128:129]
	v_cvt_pk_f32_fp8_e32 v[226:227], v79
	v_pk_fma_f32 v[128:129], v[192:193], v[224:225], v[128:129]
	v_cvt_pk_f32_fp8_sdwa v[228:229], v79 src0_sel:WORD_1
	v_pk_fma_f32 v[128:129], v[194:195], v[226:227], v[128:129]
	v_pk_fma_f32 v[128:129], v[196:197], v[228:229], v[128:129]
	buffer_load_dwordx4 v[76:79], v169, s[16:19], s27 offen
	v_add_f32_dpp v168, v132, v132 row_half_mirror row_mask:0xf bank_mask:0xf
	v_add_f32_e32 v133, v128, v129
	s_waitcnt vmcnt(37)
; #define LAS __attribute__((address_space(3)))
; __device__ __forceinline__ float red8(float v) { v += dpp_f<0xB1>(v); v += dpp_f<0x4E>(v); v += dpp_f<0x141>(v); return v; }
; __device__ __forceinline__ void kv8_issue(u32x4 (&buf)[8], __amdgpu_buffer_rsrc_t rs, int voff  , int sbase  , const int (&iv)[4], int b) {
;     const int jj = b >> 3, l0 = (b & 7) * 8;
;     const int ivb = (jj == 0) ? iv[0] : (jj == 1) ? iv[1] : (jj == 2) ? iv[2] : iv[3];
; #pragma unroll
;     for (int u = 0; u < 8; ++u) { const int si = __builtin_amdgcn_readlane(ivb, l0 + u); buf[u] = __builtin_amdgcn_raw_buffer_load_b128(rs, voff, si * 2048 + sbase, KV8_AUX); }
; }
; __device__ __forceinline__ void kv8_qk(const u32x4 (&buf)[8], const f32x2v (&q2)[8], LAS float* srow, int b, int lane) {
; #pragma unroll
;     for (int u = 0; u < 8; ++u) {
;         const u32x4 k = buf[u];
;         f32x2v s0 = q2[0] * __builtin_amdgcn_cvt_pk_f32_fp8(k.x, false), s1 = q2[1] * __builtin_amdgcn_cvt_pk_f32_fp8(k.x, true);
;         s0 = __builtin_elementwise_fma(q2[2], __builtin_amdgcn_cvt_pk_f32_fp8(k.y, false), s0); s1 = __builtin_elementwise_fma(q2[3], __builtin_amdgcn_cvt_pk_f32_fp8(k.y, true), s1);
;         s0 = __builtin_elementwise_fma(q2[4], __builtin_amdgcn_cvt_pk_f32_fp8(k.z, false), s0); s1 = __builtin_elementwise_fma(q2[5], __builtin_amdgcn_cvt_pk_f32_fp8(k.z, true), s1);
;         s0 = __builtin_elementwise_fma(q2[6], __builtin_amdgcn_cvt_pk_f32_fp8(k.w, false), s0); s1 = __builtin_elementwise_fma(q2[7], __builtin_amdgcn_cvt_pk_f32_fp8(k.w, true), s1);
;         const f32x2v t = s0 + s1;
;         const float s = red8(t.x + t.y);
;         if ((lane & 7) == 0) srow[b * 8 + u] = s;
;     }
; }
	v_cvt_pk_f32_fp8_e32 v[214:215], v80
	v_cvt_pk_f32_fp8_sdwa v[216:217], v80 src0_sel:WORD_1
	v_pk_mul_f32 v[128:129], v[214:215], v[182:183]
	v_cvt_pk_f32_fp8_e32 v[218:219], v81
	v_add_f32_dpp v133, v133, v133 quad_perm:[1,0,3,2] row_mask:0xf bank_mask:0xf
	v_pk_fma_f32 v[128:129], v[184:185], v[216:217], v[128:129]
	v_cvt_pk_f32_fp8_sdwa v[220:221], v81 src0_sel:WORD_1
	v_pk_fma_f32 v[128:129], v[186:187], v[218:219], v[128:129]
	v_cvt_pk_f32_fp8_e32 v[222:223], v82
	v_pk_fma_f32 v[128:129], v[188:189], v[220:221], v[128:129]
	v_cvt_pk_f32_fp8_sdwa v[224:225], v82 src0_sel:WORD_1
	v_add_f32_dpp v133, v133, v133 quad_perm:[2,3,0,1] row_mask:0xf bank_mask:0xf
	v_pk_fma_f32 v[128:129], v[190:191], v[222:223], v[128:129]
	v_cvt_pk_f32_fp8_e32 v[226:227], v83
	v_pk_fma_f32 v[128:129], v[192:193], v[224:225], v[128:129]
	v_cvt_pk_f32_fp8_sdwa v[228:229], v83 src0_sel:WORD_1
	v_pk_fma_f32 v[128:129], v[194:195], v[226:227], v[128:129]
	v_pk_fma_f32 v[128:129], v[196:197], v[228:229], v[128:129]
	buffer_load_dwordx4 v[80:83], v170, s[16:19], s27 offen
	v_add_f32_dpp v169, v133, v133 row_half_mirror row_mask:0xf bank_mask:0xf
	v_add_f32_e32 v132, v128, v129
	s_waitcnt vmcnt(37)
	v_cvt_pk_f32_fp8_e32 v[214:215], v84
	v_cvt_pk_f32_fp8_sdwa v[216:217], v84 src0_sel:WORD_1
	v_pk_mul_f32 v[128:129], v[214:215], v[182:183]
	v_cvt_pk_f32_fp8_e32 v[218:219], v85
	v_add_f32_dpp v132, v132, v132 quad_perm:[1,0,3,2] row_mask:0xf bank_mask:0xf
	v_pk_fma_f32 v[128:129], v[184:185], v[216:217], v[128:129]
	v_cvt_pk_f32_fp8_sdwa v[220:221], v85 src0_sel:WORD_1
	v_pk_fma_f32 v[128:129], v[186:187], v[218:219], v[128:129]
	v_cvt_pk_f32_fp8_e32 v[222:223], v86
	v_pk_fma_f32 v[128:129], v[188:189], v[220:221], v[128:129]
	v_cvt_pk_f32_fp8_sdwa v[224:225], v86 src0_sel:WORD_1
	v_add_f32_dpp v132, v132, v132 quad_perm:[2,3,0,1] row_mask:0xf bank_mask:0xf
	v_pk_fma_f32 v[128:129], v[190:191], v[222:223], v[128:129]
	v_cvt_pk_f32_fp8_e32 v[226:227], v87
	v_pk_fma_f32 v[128:129], v[192:193], v[224:225], v[128:129]
	v_cvt_pk_f32_fp8_sdwa v[228:229], v87 src0_sel:WORD_1
	v_pk_fma_f32 v[128:129], v[194:195], v[226:227], v[128:129]
	v_pk_fma_f32 v[128:129], v[196:197], v[228:229], v[128:129]
	buffer_load_dwordx4 v[84:87], v171, s[16:19], s27 offen
	v_add_f32_dpp v170, v132, v132 row_half_mirror row_mask:0xf bank_mask:0xf
	v_add_f32_e32 v133, v128, v129
	s_waitcnt vmcnt(37)
	v_cvt_pk_f32_fp8_e32 v[214:215], v88
	v_cvt_pk_f32_fp8_sdwa v[216:217], v88 src0_sel:WORD_1
	v_pk_mul_f32 v[128:129], v[214:215], v[182:183]
	v_cvt_pk_f32_fp8_e32 v[218:219], v89
	v_add_f32_dpp v133, v133, v133 quad_perm:[1,0,3,2] row_mask:0xf bank_mask:0xf
	v_pk_fma_f32 v[128:129], v[184:185], v[216:217], v[128:129]
	v_cvt_pk_f32_fp8_sdwa v[220:221], v89 src0_sel:WORD_1
	v_pk_fma_f32 v[128:129], v[186:187], v[218:219], v[128:129]
	v_cvt_pk_f32_fp8_e32 v[222:223], v90
	v_pk_fma_f32 v[128:129], v[188:189], v[220:221], v[128:129]
	v_cvt_pk_f32_fp8_sdwa v[224:225], v90 src0_sel:WORD_1
	v_add_f32_dpp v133, v133, v133 quad_perm:[2,3,0,1] row_mask:0xf bank_mask:0xf
	v_pk_fma_f32 v[128:129], v[190:191], v[222:223], v[128:129]
	v_cvt_pk_f32_fp8_e32 v[226:227], v91
	v_pk_fma_f32 v[128:129], v[192:193], v[224:225], v[128:129]
	v_cvt_pk_f32_fp8_sdwa v[228:229], v91 src0_sel:WORD_1
	v_pk_fma_f32 v[128:129], v[194:195], v[226:227], v[128:129]
	v_pk_fma_f32 v[128:129], v[196:197], v[228:229], v[128:129]
	buffer_load_dwordx4 v[88:91], v172, s[16:19], s27 offen
	v_add_f32_dpp v171, v133, v133 row_half_mirror row_mask:0xf bank_mask:0xf
	v_add_f32_e32 v132, v128, v129
	s_waitcnt vmcnt(37)
	v_cvt_pk_f32_fp8_e32 v[214:215], v92
	v_cvt_pk_f32_fp8_sdwa v[216:217], v92 src0_sel:WORD_1
	v_pk_mul_f32 v[128:129], v[214:215], v[182:183]
	v_cvt_pk_f32_fp8_e32 v[218:219], v93
	v_add_f32_dpp v132, v132, v132 quad_perm:[1,0,3,2] row_mask:0xf bank_mask:0xf
	v_pk_fma_f32 v[128:129], v[184:185], v[216:217], v[128:129]
	v_cvt_pk_f32_fp8_sdwa v[220:221], v93 src0_sel:WORD_1
	v_pk_fma_f32 v[128:129], v[186:187], v[218:219], v[128:129]
	v_cvt_pk_f32_fp8_e32 v[222:223], v94
	v_pk_fma_f32 v[128:129], v[188:189], v[220:221], v[128:129]
	v_cvt_pk_f32_fp8_sdwa v[224:225], v94 src0_sel:WORD_1
	v_add_f32_dpp v132, v132, v132 quad_perm:[2,3,0,1] row_mask:0xf bank_mask:0xf
	v_pk_fma_f32 v[128:129], v[190:191], v[222:223], v[128:129]
	v_cvt_pk_f32_fp8_e32 v[226:227], v95
	v_pk_fma_f32 v[128:129], v[192:193], v[224:225], v[128:129]
	v_cvt_pk_f32_fp8_sdwa v[228:229], v95 src0_sel:WORD_1
	v_pk_fma_f32 v[128:129], v[194:195], v[226:227], v[128:129]
	v_pk_fma_f32 v[128:129], v[196:197], v[228:229], v[128:129]
	buffer_load_dwordx4 v[92:95], v173, s[16:19], s27 offen
	v_add_f32_dpp v172, v132, v132 row_half_mirror row_mask:0xf bank_mask:0xf
	v_add_f32_e32 v133, v128, v129
	s_waitcnt vmcnt(37)
	v_cvt_pk_f32_fp8_e32 v[214:215], v96
	v_cvt_pk_f32_fp8_sdwa v[216:217], v96 src0_sel:WORD_1
	v_pk_mul_f32 v[128:129], v[214:215], v[182:183]
	v_cvt_pk_f32_fp8_e32 v[218:219], v97
	v_add_f32_dpp v133, v133, v133 quad_perm:[1,0,3,2] row_mask:0xf bank_mask:0xf
	v_pk_fma_f32 v[128:129], v[184:185], v[216:217], v[128:129]
	v_cvt_pk_f32_fp8_sdwa v[220:221], v97 src0_sel:WORD_1
	v_pk_fma_f32 v[128:129], v[186:187], v[218:219], v[128:129]
	v_cvt_pk_f32_fp8_e32 v[222:223], v98
	v_pk_fma_f32 v[128:129], v[188:189], v[220:221], v[128:129]
	v_cvt_pk_f32_fp8_sdwa v[224:225], v98 src0_sel:WORD_1
	v_add_f32_dpp v133, v133, v133 quad_perm:[2,3,0,1] row_mask:0xf bank_mask:0xf
	v_pk_fma_f32 v[128:129], v[190:191], v[222:223], v[128:129]
	v_cvt_pk_f32_fp8_e32 v[226:227], v99
	v_pk_fma_f32 v[128:129], v[192:193], v[224:225], v[128:129]
	v_cvt_pk_f32_fp8_sdwa v[228:229], v99 src0_sel:WORD_1
	v_pk_fma_f32 v[128:129], v[194:195], v[226:227], v[128:129]
	v_pk_fma_f32 v[128:129], v[196:197], v[228:229], v[128:129]
	buffer_load_dwordx4 v[96:99], v174, s[16:19], s27 offen
	v_add_f32_dpp v173, v133, v133 row_half_mirror row_mask:0xf bank_mask:0xf
	v_add_f32_e32 v132, v128, v129
	s_waitcnt vmcnt(37)
; #define LAS __attribute__((address_space(3)))
; __device__ __forceinline__ float red8(float v) { v += dpp_f<0xB1>(v); v += dpp_f<0x4E>(v); v += dpp_f<0x141>(v); return v; }
; __device__ __forceinline__ void kv8_issue(u32x4 (&buf)[8], __amdgpu_buffer_rsrc_t rs, int voff  , int sbase  , const int (&iv)[4], int b) {
;     const int jj = b >> 3, l0 = (b & 7) * 8;
;     const int ivb = (jj == 0) ? iv[0] : (jj == 1) ? iv[1] : (jj == 2) ? iv[2] : iv[3];
; #pragma unroll
;     for (int u = 0; u < 8; ++u) { const int si = __builtin_amdgcn_readlane(ivb, l0 + u); buf[u] = __builtin_amdgcn_raw_buffer_load_b128(rs, voff, si * 2048 + sbase, KV8_AUX); }
; }
; __device__ __forceinline__ void kv8_qk(const u32x4 (&buf)[8], const f32x2v (&q2)[8], LAS float* srow, int b, int lane) {
; #pragma unroll
;     for (int u = 0; u < 8; ++u) {
;         const u32x4 k = buf[u];
;         f32x2v s0 = q2[0] * __builtin_amdgcn_cvt_pk_f32_fp8(k.x, false), s1 = q2[1] * __builtin_amdgcn_cvt_pk_f32_fp8(k.x, true);
;         s0 = __builtin_elementwise_fma(q2[2], __builtin_amdgcn_cvt_pk_f32_fp8(k.y, false), s0); s1 = __builtin_elementwise_fma(q2[3], __builtin_amdgcn_cvt_pk_f32_fp8(k.y, true), s1);
;         s0 = __builtin_elementwise_fma(q2[4], __builtin_amdgcn_cvt_pk_f32_fp8(k.z, false), s0); s1 = __builtin_elementwise_fma(q2[5], __builtin_amdgcn_cvt_pk_f32_fp8(k.z, true), s1);
;         s0 = __builtin_elementwise_fma(q2[6], __builtin_amdgcn_cvt_pk_f32_fp8(k.w, false), s0); s1 = __builtin_elementwise_fma(q2[7], __builtin_amdgcn_cvt_pk_f32_fp8(k.w, true), s1);
;         const f32x2v t = s0 + s1;
;         const float s = red8(t.x + t.y);
;         if ((lane & 7) == 0) srow[b * 8 + u] = s;
;     }
; }
	v_cvt_pk_f32_fp8_e32 v[214:215], v100
	v_cvt_pk_f32_fp8_sdwa v[216:217], v100 src0_sel:WORD_1
	v_pk_mul_f32 v[128:129], v[214:215], v[182:183]
	v_cvt_pk_f32_fp8_e32 v[218:219], v101
	v_add_f32_dpp v132, v132, v132 quad_perm:[1,0,3,2] row_mask:0xf bank_mask:0xf
	v_pk_fma_f32 v[128:129], v[184:185], v[216:217], v[128:129]
	v_cvt_pk_f32_fp8_sdwa v[220:221], v101 src0_sel:WORD_1
	v_pk_fma_f32 v[128:129], v[186:187], v[218:219], v[128:129]
	v_cvt_pk_f32_fp8_e32 v[222:223], v102
	v_pk_fma_f32 v[128:129], v[188:189], v[220:221], v[128:129]
	v_cvt_pk_f32_fp8_sdwa v[224:225], v102 src0_sel:WORD_1
	v_add_f32_dpp v132, v132, v132 quad_perm:[2,3,0,1] row_mask:0xf bank_mask:0xf
	v_pk_fma_f32 v[128:129], v[190:191], v[222:223], v[128:129]
	v_cvt_pk_f32_fp8_e32 v[226:227], v103
	v_pk_fma_f32 v[128:129], v[192:193], v[224:225], v[128:129]
	v_cvt_pk_f32_fp8_sdwa v[228:229], v103 src0_sel:WORD_1
	v_pk_fma_f32 v[128:129], v[194:195], v[226:227], v[128:129]
	v_pk_fma_f32 v[128:129], v[196:197], v[228:229], v[128:129]
	buffer_load_dwordx4 v[100:103], v175, s[16:19], s27 offen
	v_add_f32_dpp v174, v132, v132 row_half_mirror row_mask:0xf bank_mask:0xf
	v_add_f32_e32 v133, v128, v129
	s_waitcnt vmcnt(37)
	v_cvt_pk_f32_fp8_e32 v[214:215], v104
	v_cvt_pk_f32_fp8_sdwa v[216:217], v104 src0_sel:WORD_1
	v_pk_mul_f32 v[128:129], v[214:215], v[182:183]
	v_cvt_pk_f32_fp8_e32 v[218:219], v105
	v_add_f32_dpp v133, v133, v133 quad_perm:[1,0,3,2] row_mask:0xf bank_mask:0xf
	v_pk_fma_f32 v[128:129], v[184:185], v[216:217], v[128:129]
	v_cvt_pk_f32_fp8_sdwa v[220:221], v105 src0_sel:WORD_1
	v_pk_fma_f32 v[128:129], v[186:187], v[218:219], v[128:129]
	v_cvt_pk_f32_fp8_e32 v[222:223], v106
	v_pk_fma_f32 v[128:129], v[188:189], v[220:221], v[128:129]
	v_cvt_pk_f32_fp8_sdwa v[224:225], v106 src0_sel:WORD_1
	v_add_f32_dpp v133, v133, v133 quad_perm:[2,3,0,1] row_mask:0xf bank_mask:0xf
	v_pk_fma_f32 v[128:129], v[190:191], v[222:223], v[128:129]
	v_cvt_pk_f32_fp8_e32 v[226:227], v107
	v_pk_fma_f32 v[128:129], v[192:193], v[224:225], v[128:129]
	v_cvt_pk_f32_fp8_sdwa v[228:229], v107 src0_sel:WORD_1
	v_pk_fma_f32 v[128:129], v[194:195], v[226:227], v[128:129]
	v_pk_fma_f32 v[128:129], v[196:197], v[228:229], v[128:129]
	buffer_load_dwordx4 v[104:107], v176, s[16:19], s27 offen
	v_add_f32_dpp v175, v133, v133 row_half_mirror row_mask:0xf bank_mask:0xf
	v_add_f32_e32 v132, v128, v129
	s_waitcnt vmcnt(37)
	v_cvt_pk_f32_fp8_e32 v[214:215], v108
	v_cvt_pk_f32_fp8_sdwa v[216:217], v108 src0_sel:WORD_1
	v_pk_mul_f32 v[128:129], v[214:215], v[182:183]
	v_cvt_pk_f32_fp8_e32 v[218:219], v109
	v_add_f32_dpp v132, v132, v132 quad_perm:[1,0,3,2] row_mask:0xf bank_mask:0xf
	v_pk_fma_f32 v[128:129], v[184:185], v[216:217], v[128:129]
	v_cvt_pk_f32_fp8_sdwa v[220:221], v109 src0_sel:WORD_1
	v_pk_fma_f32 v[128:129], v[186:187], v[218:219], v[128:129]
	v_cvt_pk_f32_fp8_e32 v[222:223], v110
	v_pk_fma_f32 v[128:129], v[188:189], v[220:221], v[128:129]
	v_cvt_pk_f32_fp8_sdwa v[224:225], v110 src0_sel:WORD_1
	v_add_f32_dpp v132, v132, v132 quad_perm:[2,3,0,1] row_mask:0xf bank_mask:0xf
	v_pk_fma_f32 v[128:129], v[190:191], v[222:223], v[128:129]
	v_cvt_pk_f32_fp8_e32 v[226:227], v111
	v_pk_fma_f32 v[128:129], v[192:193], v[224:225], v[128:129]
	v_cvt_pk_f32_fp8_sdwa v[228:229], v111 src0_sel:WORD_1
	v_pk_fma_f32 v[128:129], v[194:195], v[226:227], v[128:129]
	v_pk_fma_f32 v[128:129], v[196:197], v[228:229], v[128:129]
	buffer_load_dwordx4 v[108:111], v177, s[16:19], s27 offen
	v_add_f32_dpp v176, v132, v132 row_half_mirror row_mask:0xf bank_mask:0xf
	v_add_f32_e32 v133, v128, v129
	s_waitcnt vmcnt(37)
	v_cvt_pk_f32_fp8_e32 v[214:215], v112
	v_cvt_pk_f32_fp8_sdwa v[216:217], v112 src0_sel:WORD_1
	v_pk_mul_f32 v[128:129], v[214:215], v[182:183]
	v_cvt_pk_f32_fp8_e32 v[218:219], v113
	v_add_f32_dpp v133, v133, v133 quad_perm:[1,0,3,2] row_mask:0xf bank_mask:0xf
	v_pk_fma_f32 v[128:129], v[184:185], v[216:217], v[128:129]
	v_cvt_pk_f32_fp8_sdwa v[220:221], v113 src0_sel:WORD_1
	v_pk_fma_f32 v[128:129], v[186:187], v[218:219], v[128:129]
	v_cvt_pk_f32_fp8_e32 v[222:223], v114
	v_pk_fma_f32 v[128:129], v[188:189], v[220:221], v[128:129]
	v_cvt_pk_f32_fp8_sdwa v[224:225], v114 src0_sel:WORD_1
	v_add_f32_dpp v133, v133, v133 quad_perm:[2,3,0,1] row_mask:0xf bank_mask:0xf
	v_pk_fma_f32 v[128:129], v[190:191], v[222:223], v[128:129]
	v_cvt_pk_f32_fp8_e32 v[226:227], v115
	v_pk_fma_f32 v[128:129], v[192:193], v[224:225], v[128:129]
	v_cvt_pk_f32_fp8_sdwa v[228:229], v115 src0_sel:WORD_1
	v_pk_fma_f32 v[128:129], v[194:195], v[226:227], v[128:129]
	v_pk_fma_f32 v[128:129], v[196:197], v[228:229], v[128:129]
	buffer_load_dwordx4 v[112:115], v178, s[16:19], s27 offen
	v_add_f32_dpp v177, v133, v133 row_half_mirror row_mask:0xf bank_mask:0xf
	v_add_f32_e32 v132, v128, v129
	s_waitcnt vmcnt(37)
	v_cvt_pk_f32_fp8_e32 v[214:215], v116
	v_cvt_pk_f32_fp8_sdwa v[216:217], v116 src0_sel:WORD_1
	v_pk_mul_f32 v[128:129], v[214:215], v[182:183]
	v_cvt_pk_f32_fp8_e32 v[218:219], v117
	v_add_f32_dpp v132, v132, v132 quad_perm:[1,0,3,2] row_mask:0xf bank_mask:0xf
	v_pk_fma_f32 v[128:129], v[184:185], v[216:217], v[128:129]
	v_cvt_pk_f32_fp8_sdwa v[220:221], v117 src0_sel:WORD_1
	v_pk_fma_f32 v[128:129], v[186:187], v[218:219], v[128:129]
	v_cvt_pk_f32_fp8_e32 v[222:223], v118
	v_pk_fma_f32 v[128:129], v[188:189], v[220:221], v[128:129]
	v_cvt_pk_f32_fp8_sdwa v[224:225], v118 src0_sel:WORD_1
	v_add_f32_dpp v132, v132, v132 quad_perm:[2,3,0,1] row_mask:0xf bank_mask:0xf
	v_pk_fma_f32 v[128:129], v[190:191], v[222:223], v[128:129]
	v_cvt_pk_f32_fp8_e32 v[226:227], v119
	v_pk_fma_f32 v[128:129], v[192:193], v[224:225], v[128:129]
	v_cvt_pk_f32_fp8_sdwa v[228:229], v119 src0_sel:WORD_1
	v_pk_fma_f32 v[128:129], v[194:195], v[226:227], v[128:129]
	v_pk_fma_f32 v[128:129], v[196:197], v[228:229], v[128:129]
	buffer_load_dwordx4 v[116:119], v179, s[16:19], s27 offen
	v_add_f32_dpp v178, v132, v132 row_half_mirror row_mask:0xf bank_mask:0xf
	v_add_f32_e32 v133, v128, v129
	s_waitcnt vmcnt(37)
; #define LAS __attribute__((address_space(3)))
; __device__ __forceinline__ float red8(float v) { v += dpp_f<0xB1>(v); v += dpp_f<0x4E>(v); v += dpp_f<0x141>(v); return v; }
; __device__ __forceinline__ void kv8_issue(u32x4 (&buf)[8], __amdgpu_buffer_rsrc_t rs, int voff  , int sbase  , const int (&iv)[4], int b) {
;     const int jj = b >> 3, l0 = (b & 7) * 8;
;     const int ivb = (jj == 0) ? iv[0] : (jj == 1) ? iv[1] : (jj == 2) ? iv[2] : iv[3];
; #pragma unroll
;     for (int u = 0; u < 8; ++u) { const int si = __builtin_amdgcn_readlane(ivb, l0 + u); buf[u] = __builtin_amdgcn_raw_buffer_load_b128(rs, voff, si * 2048 + sbase, KV8_AUX); }
; }
; __device__ __forceinline__ void kv8_qk(const u32x4 (&buf)[8], const f32x2v (&q2)[8], LAS float* srow, int b, int lane) {
; #pragma unroll
;     for (int u = 0; u < 8; ++u) {
;         const u32x4 k = buf[u];
;         f32x2v s0 = q2[0] * __builtin_amdgcn_cvt_pk_f32_fp8(k.x, false), s1 = q2[1] * __builtin_amdgcn_cvt_pk_f32_fp8(k.x, true);
;         s0 = __builtin_elementwise_fma(q2[2], __builtin_amdgcn_cvt_pk_f32_fp8(k.y, false), s0); s1 = __builtin_elementwise_fma(q2[3], __builtin_amdgcn_cvt_pk_f32_fp8(k.y, true), s1);
;         s0 = __builtin_elementwise_fma(q2[4], __builtin_amdgcn_cvt_pk_f32_fp8(k.z, false), s0); s1 = __builtin_elementwise_fma(q2[5], __builtin_amdgcn_cvt_pk_f32_fp8(k.z, true), s1);
;         s0 = __builtin_elementwise_fma(q2[6], __builtin_amdgcn_cvt_pk_f32_fp8(k.w, false), s0); s1 = __builtin_elementwise_fma(q2[7], __builtin_amdgcn_cvt_pk_f32_fp8(k.w, true), s1);
;         const f32x2v t = s0 + s1;
;         const float s = red8(t.x + t.y);
;         if ((lane & 7) == 0) srow[b * 8 + u] = s;
;     }
; }
; __device__ __forceinline__ void attn_query8(const unsigned char* __restrict__ KV8, const bf16_t* __restrict__ Z, const int* __restrict__ SEL, bf16_t* __restrict__ YMIX, int t, LAS float* sbuf  ) {
;     ...
;     for (int h = 0; h < 8; ++h) {
;         float sv[4]; float mx = -__builtin_inff();
; #pragma unroll
;         for (int jj = 0; jj < 4; ++jj) { const int j = lane + 64 * jj; const float s = sbuf[h * 256 + j]; sv[jj] = (j < nsel) ? s : -__builtin_inff(); mx = fmaxf(mx, sv[jj]); }
	v_cvt_pk_f32_fp8_e32 v[214:215], v120
	v_cvt_pk_f32_fp8_sdwa v[216:217], v120 src0_sel:WORD_1
	v_pk_mul_f32 v[128:129], v[214:215], v[182:183]
	v_cvt_pk_f32_fp8_e32 v[218:219], v121
	v_add_f32_dpp v133, v133, v133 quad_perm:[1,0,3,2] row_mask:0xf bank_mask:0xf
	v_pk_fma_f32 v[128:129], v[184:185], v[216:217], v[128:129]
	v_cvt_pk_f32_fp8_sdwa v[220:221], v121 src0_sel:WORD_1
	v_pk_fma_f32 v[128:129], v[186:187], v[218:219], v[128:129]
	v_cvt_pk_f32_fp8_e32 v[222:223], v122
	v_pk_fma_f32 v[128:129], v[188:189], v[220:221], v[128:129]
	v_cvt_pk_f32_fp8_sdwa v[224:225], v122 src0_sel:WORD_1
	v_add_f32_dpp v133, v133, v133 quad_perm:[2,3,0,1] row_mask:0xf bank_mask:0xf
	v_pk_fma_f32 v[128:129], v[190:191], v[222:223], v[128:129]
	v_cvt_pk_f32_fp8_e32 v[226:227], v123
	v_pk_fma_f32 v[128:129], v[192:193], v[224:225], v[128:129]
	v_cvt_pk_f32_fp8_sdwa v[228:229], v123 src0_sel:WORD_1
	v_pk_fma_f32 v[128:129], v[194:195], v[226:227], v[128:129]
	v_pk_fma_f32 v[128:129], v[196:197], v[228:229], v[128:129]
	buffer_load_dwordx4 v[120:123], v180, s[16:19], s27 offen
	v_add_f32_dpp v179, v133, v133 row_half_mirror row_mask:0xf bank_mask:0xf
	v_add_f32_e32 v132, v128, v129
	s_waitcnt vmcnt(37)
	v_cvt_pk_f32_fp8_e32 v[214:215], v124
	v_cvt_pk_f32_fp8_sdwa v[216:217], v124 src0_sel:WORD_1
	v_pk_mul_f32 v[128:129], v[214:215], v[182:183]
	v_cvt_pk_f32_fp8_e32 v[218:219], v125
	v_add_f32_dpp v132, v132, v132 quad_perm:[1,0,3,2] row_mask:0xf bank_mask:0xf
	v_pk_fma_f32 v[128:129], v[184:185], v[216:217], v[128:129]
	v_cvt_pk_f32_fp8_sdwa v[220:221], v125 src0_sel:WORD_1
	v_pk_fma_f32 v[128:129], v[186:187], v[218:219], v[128:129]
	v_cvt_pk_f32_fp8_e32 v[222:223], v126
	v_pk_fma_f32 v[128:129], v[188:189], v[220:221], v[128:129]
	v_cvt_pk_f32_fp8_sdwa v[224:225], v126 src0_sel:WORD_1
	v_add_f32_dpp v132, v132, v132 quad_perm:[2,3,0,1] row_mask:0xf bank_mask:0xf
	v_pk_fma_f32 v[128:129], v[190:191], v[222:223], v[128:129]
	v_cvt_pk_f32_fp8_e32 v[226:227], v127
	v_pk_fma_f32 v[128:129], v[192:193], v[224:225], v[128:129]
	v_cvt_pk_f32_fp8_sdwa v[228:229], v127 src0_sel:WORD_1
	v_pk_fma_f32 v[128:129], v[194:195], v[226:227], v[128:129]
	v_pk_fma_f32 v[128:129], v[196:197], v[228:229], v[128:129]
	buffer_load_dwordx4 v[124:127], v181, s[16:19], s27 offen
	v_add_f32_dpp v180, v132, v132 row_half_mirror row_mask:0xf bank_mask:0xf
	v_add_f32_e32 v133, v128, v129
	s_nop 1
	v_add_f32_dpp v133, v133, v133 quad_perm:[1,0,3,2] row_mask:0xf bank_mask:0xf
	s_nop 1
	v_add_f32_dpp v133, v133, v133 quad_perm:[2,3,0,1] row_mask:0xf bank_mask:0xf
	s_nop 1
	v_add_f32_dpp v181, v133, v133 row_half_mirror row_mask:0xf bank_mask:0xf
	s_cmpk_eq_i32 s4, 0x100
	s_cbranch_scc1 .Latt_nomask
	v_cmp_lt_i32_e32 vcc, 0, v143
	s_nop 1
	v_cndmask_b32_e32 v150, v142, v150, vcc
	v_cmp_lt_i32_e32 vcc, 8, v143
	s_nop 1
	v_cndmask_b32_e32 v151, v142, v151, vcc
	v_cmp_lt_i32_e32 vcc, 16, v143
	s_nop 1
	v_cndmask_b32_e32 v152, v142, v152, vcc
	v_cmp_lt_i32_e32 vcc, 24, v143
	s_nop 1
	v_cndmask_b32_e32 v153, v142, v153, vcc
	v_cmp_lt_i32_e32 vcc, 32, v143
	s_nop 1
	v_cndmask_b32_e32 v154, v142, v154, vcc
	v_cmp_lt_i32_e32 vcc, 40, v143
	s_nop 1
	v_cndmask_b32_e32 v155, v142, v155, vcc
	v_cmp_lt_i32_e32 vcc, 48, v143
	s_nop 1
	v_cndmask_b32_e32 v156, v142, v156, vcc
	v_cmp_lt_i32_e32 vcc, 56, v143
	s_nop 1
	v_cndmask_b32_e32 v157, v142, v157, vcc
	v_cmp_lt_i32_e32 vcc, 64, v143
	s_nop 1
	v_cndmask_b32_e32 v158, v142, v158, vcc
	v_cmp_lt_i32_e32 vcc, 0x48, v143
	s_nop 1
	v_cndmask_b32_e32 v159, v142, v159, vcc
	v_cmp_lt_i32_e32 vcc, 0x50, v143
	s_nop 1
	v_cndmask_b32_e32 v160, v142, v160, vcc
	v_cmp_lt_i32_e32 vcc, 0x58, v143
	s_nop 1
	v_cndmask_b32_e32 v161, v142, v161, vcc
	v_cmp_lt_i32_e32 vcc, 0x60, v143
	s_nop 1
	v_cndmask_b32_e32 v162, v142, v162, vcc
	v_cmp_lt_i32_e32 vcc, 0x68, v143
	s_nop 1
	v_cndmask_b32_e32 v163, v142, v163, vcc
	v_cmp_lt_i32_e32 vcc, 0x70, v143
	s_nop 1
	v_cndmask_b32_e32 v164, v142, v164, vcc
	v_cmp_lt_i32_e32 vcc, 0x78, v143
	s_nop 1
	v_cndmask_b32_e32 v165, v142, v165, vcc
	v_cmp_lt_i32_e32 vcc, 0x80, v143
	s_nop 1
	v_cndmask_b32_e32 v166, v142, v166, vcc
	v_cmp_lt_i32_e32 vcc, 0x88, v143
	s_nop 1
	v_cndmask_b32_e32 v167, v142, v167, vcc
	v_cmp_lt_i32_e32 vcc, 0x90, v143
	s_nop 1
	v_cndmask_b32_e32 v168, v142, v168, vcc
	v_cmp_lt_i32_e32 vcc, 0x98, v143
	s_nop 1
	v_cndmask_b32_e32 v169, v142, v169, vcc
	v_cmp_lt_i32_e32 vcc, 0xa0, v143
	s_nop 1
	v_cndmask_b32_e32 v170, v142, v170, vcc
	v_cmp_lt_i32_e32 vcc, 0xa8, v143
	s_nop 1
	v_cndmask_b32_e32 v171, v142, v171, vcc
	v_cmp_lt_i32_e32 vcc, 0xb0, v143
	s_nop 1
	v_cndmask_b32_e32 v172, v142, v172, vcc
	v_cmp_lt_i32_e32 vcc, 0xb8, v143
	s_nop 1
	v_cndmask_b32_e32 v173, v142, v173, vcc
	v_cmp_lt_i32_e32 vcc, 0xc0, v143
	s_nop 1
	v_cndmask_b32_e32 v174, v142, v174, vcc
	v_cmp_lt_i32_e32 vcc, 0xc8, v143
	s_nop 1
	v_cndmask_b32_e32 v175, v142, v175, vcc
	v_cmp_lt_i32_e32 vcc, 0xd0, v143
	s_nop 1
	v_cndmask_b32_e32 v176, v142, v176, vcc
	v_cmp_lt_i32_e32 vcc, 0xd8, v143
	s_nop 1
	v_cndmask_b32_e32 v177, v142, v177, vcc
	v_cmp_lt_i32_e32 vcc, 0xe0, v143
	s_nop 1
	v_cndmask_b32_e32 v178, v142, v178, vcc
	v_cmp_lt_i32_e32 vcc, 0xe8, v143
	s_nop 1
	v_cndmask_b32_e32 v179, v142, v179, vcc
	v_cmp_lt_i32_e32 vcc, 0xf0, v143
	s_nop 1
	v_cndmask_b32_e32 v180, v142, v180, vcc
	v_cmp_lt_i32_e32 vcc, 0xf8, v143
	s_nop 1
	v_cndmask_b32_e32 v181, v142, v181, vcc
; #define LAS __attribute__((address_space(3)))
; __device__ __forceinline__ void kv8_pv(const u32x4 (&buf)[8], f32x2v (&o2)[8], const LAS float* srow, int b) {
;     const LAS f32x4* p4 = (const LAS f32x4*)(srow + b * 8);
;     const f32x4 p0 = p4[0], p1 = p4[1];
;     const float p[8] = {p0.x, p0.y, p0.z, p0.w, p1.x, p1.y, p1.z, p1.w};
; #pragma unroll
;     for (int u = 0; u < 8; ++u) {
;         const u32x4 v = buf[u]; const f32x2v pp = {p[u], p[u]};
;         o2[0] = __builtin_elementwise_fma(pp, __builtin_amdgcn_cvt_pk_f32_fp8(v.x, false), o2[0]); o2[1] = __builtin_elementwise_fma(pp, __builtin_amdgcn_cvt_pk_f32_fp8(v.x, true), o2[1]);
;         o2[2] = __builtin_elementwise_fma(pp, __builtin_amdgcn_cvt_pk_f32_fp8(v.y, false), o2[2]); o2[3] = __builtin_elementwise_fma(pp, __builtin_amdgcn_cvt_pk_f32_fp8(v.y, true), o2[3]);
;         o2[4] = __builtin_elementwise_fma(pp, __builtin_amdgcn_cvt_pk_f32_fp8(v.z, false), o2[4]); o2[5] = __builtin_elementwise_fma(pp, __builtin_amdgcn_cvt_pk_f32_fp8(v.z, true), o2[5]);
;         o2[6] = __builtin_elementwise_fma(pp, __builtin_amdgcn_cvt_pk_f32_fp8(v.w, false), o2[6]); o2[7] = __builtin_elementwise_fma(pp, __builtin_amdgcn_cvt_pk_f32_fp8(v.w, true), o2[7]);
;     }
; }
; __device__ __forceinline__ void attn_query8(const unsigned char* __restrict__ KV8, const bf16_t* __restrict__ Z, const int* __restrict__ SEL, bf16_t* __restrict__ YMIX, int t, LAS float* sbuf  ) {
;     ...
;     for (int h = 0; h < 8; ++h) {
;         float sv[4]; float mx = -__builtin_inff();
; #pragma unroll
;         for (int jj = 0; jj < 4; ++jj) { const int j = lane + 64 * jj; const float s = sbuf[h * 256 + j]; sv[jj] = (j < nsel) ? s : -__builtin_inff(); mx = fmaxf(mx, sv[jj]); }
;         mx = wave_max(mx); float sm = 0.f;
; #pragma unroll
;         for (int jj = 0; jj < 4; ++jj) { const int j = lane + 64 * jj; sv[jj] = (j < nsel) ? __expf(sv[jj] - mx) : 0.f; sm += sv[jj]; }
;         sm = wave_sum(sm); const float inv = 1.f / sm;
; #pragma unroll
;         for (int jj = 0; jj < 4; ++jj) sbuf[h * 256 + lane + 64 * jj] = sv[jj] * inv;
;     }
.Latt_nomask:
	v_max3_f32 v134, v150, v151, v152
	v_max3_f32 v134, v134, v153, v154
	v_max3_f32 v134, v134, v155, v156
	v_max3_f32 v134, v134, v157, v158
	v_max3_f32 v134, v134, v159, v160
	v_max3_f32 v134, v134, v161, v162
	v_max3_f32 v134, v134, v163, v164
	v_max3_f32 v134, v134, v165, v166
	v_max3_f32 v134, v134, v167, v168
	v_max3_f32 v134, v134, v169, v170
	v_max3_f32 v134, v134, v171, v172
	v_max3_f32 v134, v134, v173, v174
	v_max3_f32 v134, v134, v175, v176
	v_max3_f32 v134, v134, v177, v178
	v_max3_f32 v134, v134, v179, v180
	v_max_f32_e32 v134, v134, v181
	s_nop 1
	v_mov_b32_dpp v135, v134 row_ror:8 row_mask:0xf bank_mask:0xf
	s_nop 0
	v_max_f32_e32 v134, v134, v135
	ds_bpermute_b32 v135, v140, v134
	s_waitcnt lgkmcnt(0)
	v_max_f32_e32 v134, v134, v135
	ds_bpermute_b32 v135, v141, v134
	s_waitcnt lgkmcnt(0)
	v_max_f32_e32 v134, v134, v135
	v_mul_f32_e32 v134, 0xbfb8aa3b, v134
	v_fma_f32 v150, v150, s28, v134
	v_fma_f32 v151, v151, s28, v134
	v_fma_f32 v152, v152, s28, v134
	v_fma_f32 v153, v153, s28, v134
	v_fma_f32 v154, v154, s28, v134
	v_fma_f32 v155, v155, s28, v134
	v_fma_f32 v156, v156, s28, v134
	v_fma_f32 v157, v157, s28, v134
	v_fma_f32 v158, v158, s28, v134
	v_fma_f32 v159, v159, s28, v134
	v_fma_f32 v160, v160, s28, v134
	v_fma_f32 v161, v161, s28, v134
	v_fma_f32 v162, v162, s28, v134
	v_fma_f32 v163, v163, s28, v134
	v_fma_f32 v164, v164, s28, v134
	v_fma_f32 v165, v165, s28, v134
	v_fma_f32 v166, v166, s28, v134
	v_fma_f32 v167, v167, s28, v134
	v_fma_f32 v168, v168, s28, v134
	v_fma_f32 v169, v169, s28, v134
	v_fma_f32 v170, v170, s28, v134
	v_fma_f32 v171, v171, s28, v134
	v_fma_f32 v172, v172, s28, v134
	v_fma_f32 v173, v173, s28, v134
	v_fma_f32 v174, v174, s28, v134
	v_fma_f32 v175, v175, s28, v134
	v_fma_f32 v176, v176, s28, v134
	v_fma_f32 v177, v177, s28, v134
	v_fma_f32 v178, v178, s28, v134
	v_fma_f32 v179, v179, s28, v134
	v_fma_f32 v180, v180, s28, v134
	v_fma_f32 v181, v181, s28, v134
	v_exp_f32_e32 v150, v150
	v_exp_f32_e32 v151, v151
	v_exp_f32_e32 v152, v152
	v_exp_f32_e32 v153, v153
	v_exp_f32_e32 v154, v154
	v_exp_f32_e32 v155, v155
	v_exp_f32_e32 v156, v156
	v_exp_f32_e32 v157, v157
	v_exp_f32_e32 v158, v158
	v_exp_f32_e32 v159, v159
	v_exp_f32_e32 v160, v160
	v_exp_f32_e32 v161, v161
	v_exp_f32_e32 v162, v162
	v_exp_f32_e32 v163, v163
	v_exp_f32_e32 v164, v164
	v_exp_f32_e32 v165, v165
	v_exp_f32_e32 v166, v166
	v_exp_f32_e32 v167, v167
	v_exp_f32_e32 v168, v168
	v_exp_f32_e32 v169, v169
	v_exp_f32_e32 v170, v170
	v_exp_f32_e32 v171, v171
	v_exp_f32_e32 v172, v172
	v_exp_f32_e32 v173, v173
	v_exp_f32_e32 v174, v174
	v_exp_f32_e32 v175, v175
	v_exp_f32_e32 v176, v176
	v_exp_f32_e32 v177, v177
	v_exp_f32_e32 v178, v178
	v_exp_f32_e32 v179, v179
	v_exp_f32_e32 v180, v180
	v_exp_f32_e32 v181, v181
	s_nop 0
	v_add_f32_e32 v134, v150, v151
	v_add_f32_e32 v134, v134, v152
	v_add_f32_e32 v134, v134, v153
	v_add_f32_e32 v134, v134, v154
	v_add_f32_e32 v134, v134, v155
	v_add_f32_e32 v134, v134, v156
	v_add_f32_e32 v134, v134, v157
	v_add_f32_e32 v134, v134, v158
	v_add_f32_e32 v134, v134, v159
	v_add_f32_e32 v134, v134, v160
	v_add_f32_e32 v134, v134, v161
	v_add_f32_e32 v134, v134, v162
	v_add_f32_e32 v134, v134, v163
	v_add_f32_e32 v134, v134, v164
	v_add_f32_e32 v134, v134, v165
	v_add_f32_e32 v134, v134, v166
	v_add_f32_e32 v134, v134, v167
	v_add_f32_e32 v134, v134, v168
	v_add_f32_e32 v134, v134, v169
	v_add_f32_e32 v134, v134, v170
	v_add_f32_e32 v134, v134, v171
	v_add_f32_e32 v134, v134, v172
	v_add_f32_e32 v134, v134, v173
	v_add_f32_e32 v134, v134, v174
	v_add_f32_e32 v134, v134, v175
	v_add_f32_e32 v134, v134, v176
	v_add_f32_e32 v134, v134, v177
	v_add_f32_e32 v134, v134, v178
	v_add_f32_e32 v134, v134, v179
	v_add_f32_e32 v134, v134, v180
	v_add_f32_e32 v134, v134, v181
	s_nop 1
	v_mov_b32_dpp v135, v134 row_ror:8 row_mask:0xf bank_mask:0xf
	s_nop 0
	v_add_f32_e32 v134, v134, v135
	ds_bpermute_b32 v135, v140, v134
	s_waitcnt lgkmcnt(0)
	v_add_f32_e32 v134, v134, v135
	ds_bpermute_b32 v135, v141, v134
	s_waitcnt lgkmcnt(0)
	v_add_f32_e32 v134, v134, v135
	v_div_scale_f32 v132, s[8:9], v134, v134, 1.0
	v_rcp_f32_e32 v135, v132
	v_div_scale_f32 v133, vcc, 1.0, v134, 1.0
	v_fma_f32 v136, -v132, v135, 1.0
	v_fmac_f32_e32 v135, v136, v135
	v_mul_f32_e32 v136, v133, v135
	v_fma_f32 v137, -v132, v136, v133
	v_fmac_f32_e32 v136, v137, v135
	v_fma_f32 v132, -v132, v136, v133
	s_nop 1
	v_div_fmas_f32 v132, v132, v135, v136
	v_div_fixup_f32 v134, v132, v134, 1.0
	v_mov_b32_e32 v149, v134
	s_waitcnt vmcnt(31)
	ds_write_b32 v148, v240 offset:0
	ds_write_b32 v148, v241 offset:32
	ds_write_b32 v148, v242 offset:64
	ds_write_b32 v148, v243 offset:96
	v_cvt_pk_f32_fp8_e32 v[214:215], v0
	v_cvt_pk_f32_fp8_sdwa v[216:217], v0 src0_sel:WORD_1
	v_pk_mul_f32 v[198:199], v[150:151], v[214:215] op_sel_hi:[0,1]
	v_pk_mul_f32 v[200:201], v[150:151], v[216:217] op_sel_hi:[0,1]
	v_cvt_pk_f32_fp8_e32 v[218:219], v1
	v_cvt_pk_f32_fp8_sdwa v[220:221], v1 src0_sel:WORD_1
	v_pk_mul_f32 v[202:203], v[150:151], v[218:219] op_sel_hi:[0,1]
	v_pk_mul_f32 v[204:205], v[150:151], v[220:221] op_sel_hi:[0,1]
	v_cvt_pk_f32_fp8_e32 v[214:215], v2
	v_cvt_pk_f32_fp8_sdwa v[216:217], v2 src0_sel:WORD_1
	v_pk_mul_f32 v[206:207], v[150:151], v[214:215] op_sel_hi:[0,1]
	v_pk_mul_f32 v[208:209], v[150:151], v[216:217] op_sel_hi:[0,1]
	v_cvt_pk_f32_fp8_e32 v[218:219], v3
	v_cvt_pk_f32_fp8_sdwa v[220:221], v3 src0_sel:WORD_1
	v_pk_mul_f32 v[210:211], v[150:151], v[218:219] op_sel_hi:[0,1]
	v_pk_mul_f32 v[212:213], v[150:151], v[220:221] op_sel_hi:[0,1]
	s_waitcnt vmcnt(30)
; #define LAS __attribute__((address_space(3)))
; __device__ __forceinline__ void kv8_issue(u32x4 (&buf)[8], __amdgpu_buffer_rsrc_t rs, int voff  , int sbase  , const int (&iv)[4], int b) {
;     const int jj = b >> 3, l0 = (b & 7) * 8;
;     const int ivb = (jj == 0) ? iv[0] : (jj == 1) ? iv[1] : (jj == 2) ? iv[2] : iv[3];
; #pragma unroll
;     for (int u = 0; u < 8; ++u) { const int si = __builtin_amdgcn_readlane(ivb, l0 + u); buf[u] = __builtin_amdgcn_raw_buffer_load_b128(rs, voff, si * 2048 + sbase, KV8_AUX); }
; }
; __device__ __forceinline__ void kv8_pv(const u32x4 (&buf)[8], f32x2v (&o2)[8], const LAS float* srow, int b) {
;     const LAS f32x4* p4 = (const LAS f32x4*)(srow + b * 8);
;     const f32x4 p0 = p4[0], p1 = p4[1];
;     const float p[8] = {p0.x, p0.y, p0.z, p0.w, p1.x, p1.y, p1.z, p1.w};
; #pragma unroll
;     for (int u = 0; u < 8; ++u) {
;         const u32x4 v = buf[u]; const f32x2v pp = {p[u], p[u]};
;         o2[0] = __builtin_elementwise_fma(pp, __builtin_amdgcn_cvt_pk_f32_fp8(v.x, false), o2[0]); o2[1] = __builtin_elementwise_fma(pp, __builtin_amdgcn_cvt_pk_f32_fp8(v.x, true), o2[1]);
;         o2[2] = __builtin_elementwise_fma(pp, __builtin_amdgcn_cvt_pk_f32_fp8(v.y, false), o2[2]); o2[3] = __builtin_elementwise_fma(pp, __builtin_amdgcn_cvt_pk_f32_fp8(v.y, true), o2[3]);
;         o2[4] = __builtin_elementwise_fma(pp, __builtin_amdgcn_cvt_pk_f32_fp8(v.z, false), o2[4]); o2[5] = __builtin_elementwise_fma(pp, __builtin_amdgcn_cvt_pk_f32_fp8(v.z, true), o2[5]);
;         o2[6] = __builtin_elementwise_fma(pp, __builtin_amdgcn_cvt_pk_f32_fp8(v.w, false), o2[6]); o2[7] = __builtin_elementwise_fma(pp, __builtin_amdgcn_cvt_pk_f32_fp8(v.w, true), o2[7]);
;     }
; }
	v_cvt_pk_f32_fp8_e32 v[214:215], v4
	v_cvt_pk_f32_fp8_sdwa v[216:217], v4 src0_sel:WORD_1
	v_pk_fma_f32 v[198:199], v[150:151], v[214:215], v[198:199] op_sel:[1,0,0]
	v_pk_fma_f32 v[200:201], v[150:151], v[216:217], v[200:201] op_sel:[1,0,0]
	v_cvt_pk_f32_fp8_e32 v[218:219], v5
	v_cvt_pk_f32_fp8_sdwa v[220:221], v5 src0_sel:WORD_1
	v_pk_fma_f32 v[202:203], v[150:151], v[218:219], v[202:203] op_sel:[1,0,0]
	v_pk_fma_f32 v[204:205], v[150:151], v[220:221], v[204:205] op_sel:[1,0,0]
	v_cvt_pk_f32_fp8_e32 v[214:215], v6
	v_cvt_pk_f32_fp8_sdwa v[216:217], v6 src0_sel:WORD_1
	v_pk_fma_f32 v[206:207], v[150:151], v[214:215], v[206:207] op_sel:[1,0,0]
	v_pk_fma_f32 v[208:209], v[150:151], v[216:217], v[208:209] op_sel:[1,0,0]
	v_cvt_pk_f32_fp8_e32 v[218:219], v7
	v_cvt_pk_f32_fp8_sdwa v[220:221], v7 src0_sel:WORD_1
	v_pk_fma_f32 v[210:211], v[150:151], v[218:219], v[210:211] op_sel:[1,0,0]
	v_pk_fma_f32 v[212:213], v[150:151], v[220:221], v[212:213] op_sel:[1,0,0]
	s_waitcnt vmcnt(29)
	v_cvt_pk_f32_fp8_e32 v[214:215], v8
	v_cvt_pk_f32_fp8_sdwa v[216:217], v8 src0_sel:WORD_1
	v_pk_fma_f32 v[198:199], v[152:153], v[214:215], v[198:199] op_sel_hi:[0,1,1]
	v_pk_fma_f32 v[200:201], v[152:153], v[216:217], v[200:201] op_sel_hi:[0,1,1]
	v_cvt_pk_f32_fp8_e32 v[218:219], v9
	v_cvt_pk_f32_fp8_sdwa v[220:221], v9 src0_sel:WORD_1
	v_pk_fma_f32 v[202:203], v[152:153], v[218:219], v[202:203] op_sel_hi:[0,1,1]
	v_pk_fma_f32 v[204:205], v[152:153], v[220:221], v[204:205] op_sel_hi:[0,1,1]
	v_cvt_pk_f32_fp8_e32 v[214:215], v10
	v_cvt_pk_f32_fp8_sdwa v[216:217], v10 src0_sel:WORD_1
	v_pk_fma_f32 v[206:207], v[152:153], v[214:215], v[206:207] op_sel_hi:[0,1,1]
	v_pk_fma_f32 v[208:209], v[152:153], v[216:217], v[208:209] op_sel_hi:[0,1,1]
	v_cvt_pk_f32_fp8_e32 v[218:219], v11
	v_cvt_pk_f32_fp8_sdwa v[220:221], v11 src0_sel:WORD_1
	v_pk_fma_f32 v[210:211], v[152:153], v[218:219], v[210:211] op_sel_hi:[0,1,1]
	v_pk_fma_f32 v[212:213], v[152:153], v[220:221], v[212:213] op_sel_hi:[0,1,1]
	s_waitcnt vmcnt(28)
	v_cvt_pk_f32_fp8_e32 v[214:215], v12
	v_cvt_pk_f32_fp8_sdwa v[216:217], v12 src0_sel:WORD_1
	v_pk_fma_f32 v[198:199], v[152:153], v[214:215], v[198:199] op_sel:[1,0,0]
	v_pk_fma_f32 v[200:201], v[152:153], v[216:217], v[200:201] op_sel:[1,0,0]
	v_cvt_pk_f32_fp8_e32 v[218:219], v13
	v_cvt_pk_f32_fp8_sdwa v[220:221], v13 src0_sel:WORD_1
	v_pk_fma_f32 v[202:203], v[152:153], v[218:219], v[202:203] op_sel:[1,0,0]
	v_pk_fma_f32 v[204:205], v[152:153], v[220:221], v[204:205] op_sel:[1,0,0]
	v_cvt_pk_f32_fp8_e32 v[214:215], v14
	v_cvt_pk_f32_fp8_sdwa v[216:217], v14 src0_sel:WORD_1
	v_pk_fma_f32 v[206:207], v[152:153], v[214:215], v[206:207] op_sel:[1,0,0]
	v_pk_fma_f32 v[208:209], v[152:153], v[216:217], v[208:209] op_sel:[1,0,0]
	v_cvt_pk_f32_fp8_e32 v[218:219], v15
	v_cvt_pk_f32_fp8_sdwa v[220:221], v15 src0_sel:WORD_1
	v_pk_fma_f32 v[210:211], v[152:153], v[218:219], v[210:211] op_sel:[1,0,0]
	v_pk_fma_f32 v[212:213], v[152:153], v[220:221], v[212:213] op_sel:[1,0,0]
	ds_read_b128 v[150:153], v139 offset:0
	s_waitcnt vmcnt(27)
	v_cvt_pk_f32_fp8_e32 v[214:215], v16
	v_cvt_pk_f32_fp8_sdwa v[216:217], v16 src0_sel:WORD_1
	v_pk_fma_f32 v[198:199], v[154:155], v[214:215], v[198:199] op_sel_hi:[0,1,1]
	v_pk_fma_f32 v[200:201], v[154:155], v[216:217], v[200:201] op_sel_hi:[0,1,1]
	v_cvt_pk_f32_fp8_e32 v[218:219], v17
	v_cvt_pk_f32_fp8_sdwa v[220:221], v17 src0_sel:WORD_1
	v_pk_fma_f32 v[202:203], v[154:155], v[218:219], v[202:203] op_sel_hi:[0,1,1]
	v_pk_fma_f32 v[204:205], v[154:155], v[220:221], v[204:205] op_sel_hi:[0,1,1]
	v_cvt_pk_f32_fp8_e32 v[214:215], v18
	v_cvt_pk_f32_fp8_sdwa v[216:217], v18 src0_sel:WORD_1
	v_pk_fma_f32 v[206:207], v[154:155], v[214:215], v[206:207] op_sel_hi:[0,1,1]
	v_pk_fma_f32 v[208:209], v[154:155], v[216:217], v[208:209] op_sel_hi:[0,1,1]
	v_cvt_pk_f32_fp8_e32 v[218:219], v19
	v_cvt_pk_f32_fp8_sdwa v[220:221], v19 src0_sel:WORD_1
	v_pk_fma_f32 v[210:211], v[154:155], v[218:219], v[210:211] op_sel_hi:[0,1,1]
	v_pk_fma_f32 v[212:213], v[154:155], v[220:221], v[212:213] op_sel_hi:[0,1,1]
	s_waitcnt vmcnt(26)
	v_cvt_pk_f32_fp8_e32 v[214:215], v20
	v_cvt_pk_f32_fp8_sdwa v[216:217], v20 src0_sel:WORD_1
	v_pk_fma_f32 v[198:199], v[154:155], v[214:215], v[198:199] op_sel:[1,0,0]
	v_pk_fma_f32 v[200:201], v[154:155], v[216:217], v[200:201] op_sel:[1,0,0]
	v_cvt_pk_f32_fp8_e32 v[218:219], v21
	v_cvt_pk_f32_fp8_sdwa v[220:221], v21 src0_sel:WORD_1
	v_pk_fma_f32 v[202:203], v[154:155], v[218:219], v[202:203] op_sel:[1,0,0]
	v_pk_fma_f32 v[204:205], v[154:155], v[220:221], v[204:205] op_sel:[1,0,0]
	v_cvt_pk_f32_fp8_e32 v[214:215], v22
	v_cvt_pk_f32_fp8_sdwa v[216:217], v22 src0_sel:WORD_1
	v_pk_fma_f32 v[206:207], v[154:155], v[214:215], v[206:207] op_sel:[1,0,0]
	v_pk_fma_f32 v[208:209], v[154:155], v[216:217], v[208:209] op_sel:[1,0,0]
	v_cvt_pk_f32_fp8_e32 v[218:219], v23
	v_cvt_pk_f32_fp8_sdwa v[220:221], v23 src0_sel:WORD_1
	v_pk_fma_f32 v[210:211], v[154:155], v[218:219], v[210:211] op_sel:[1,0,0]
	v_pk_fma_f32 v[212:213], v[154:155], v[220:221], v[212:213] op_sel:[1,0,0]
	s_waitcnt lgkmcnt(0)
	v_lshl_add_u32 v150, v150, 8, v138
	v_lshl_add_u32 v151, v151, 8, v138
	v_lshl_add_u32 v152, v152, 8, v138
	v_lshl_add_u32 v153, v153, 8, v138
	buffer_load_dwordx4 v[0:3], v150, s[16:19], s26 offen
	buffer_load_dwordx4 v[4:7], v151, s[16:19], s26 offen
	buffer_load_dwordx4 v[8:11], v152, s[16:19], s26 offen
	buffer_load_dwordx4 v[12:15], v153, s[16:19], s26 offen
	s_waitcnt vmcnt(29)
; #define LAS __attribute__((address_space(3)))
; __device__ __forceinline__ void kv8_issue(u32x4 (&buf)[8], __amdgpu_buffer_rsrc_t rs, int voff  , int sbase  , const int (&iv)[4], int b) {
;     const int jj = b >> 3, l0 = (b & 7) * 8;
;     const int ivb = (jj == 0) ? iv[0] : (jj == 1) ? iv[1] : (jj == 2) ? iv[2] : iv[3];
; #pragma unroll
;     for (int u = 0; u < 8; ++u) { const int si = __builtin_amdgcn_readlane(ivb, l0 + u); buf[u] = __builtin_amdgcn_raw_buffer_load_b128(rs, voff, si * 2048 + sbase, KV8_AUX); }
; }
; __device__ __forceinline__ void kv8_pv(const u32x4 (&buf)[8], f32x2v (&o2)[8], const LAS float* srow, int b) {
;     const LAS f32x4* p4 = (const LAS f32x4*)(srow + b * 8);
;     const f32x4 p0 = p4[0], p1 = p4[1];
;     const float p[8] = {p0.x, p0.y, p0.z, p0.w, p1.x, p1.y, p1.z, p1.w};
; #pragma unroll
;     for (int u = 0; u < 8; ++u) {
;         const u32x4 v = buf[u]; const f32x2v pp = {p[u], p[u]};
;         o2[0] = __builtin_elementwise_fma(pp, __builtin_amdgcn_cvt_pk_f32_fp8(v.x, false), o2[0]); o2[1] = __builtin_elementwise_fma(pp, __builtin_amdgcn_cvt_pk_f32_fp8(v.x, true), o2[1]);
;         o2[2] = __builtin_elementwise_fma(pp, __builtin_amdgcn_cvt_pk_f32_fp8(v.y, false), o2[2]); o2[3] = __builtin_elementwise_fma(pp, __builtin_amdgcn_cvt_pk_f32_fp8(v.y, true), o2[3]);
;         o2[4] = __builtin_elementwise_fma(pp, __builtin_amdgcn_cvt_pk_f32_fp8(v.z, false), o2[4]); o2[5] = __builtin_elementwise_fma(pp, __builtin_amdgcn_cvt_pk_f32_fp8(v.z, true), o2[5]);
;         o2[6] = __builtin_elementwise_fma(pp, __builtin_amdgcn_cvt_pk_f32_fp8(v.w, false), o2[6]); o2[7] = __builtin_elementwise_fma(pp, __builtin_amdgcn_cvt_pk_f32_fp8(v.w, true), o2[7]);
;     }
; }
	v_cvt_pk_f32_fp8_e32 v[214:215], v24
	v_cvt_pk_f32_fp8_sdwa v[216:217], v24 src0_sel:WORD_1
	v_pk_fma_f32 v[198:199], v[156:157], v[214:215], v[198:199] op_sel_hi:[0,1,1]
	v_pk_fma_f32 v[200:201], v[156:157], v[216:217], v[200:201] op_sel_hi:[0,1,1]
	v_cvt_pk_f32_fp8_e32 v[218:219], v25
	v_cvt_pk_f32_fp8_sdwa v[220:221], v25 src0_sel:WORD_1
	v_pk_fma_f32 v[202:203], v[156:157], v[218:219], v[202:203] op_sel_hi:[0,1,1]
	v_pk_fma_f32 v[204:205], v[156:157], v[220:221], v[204:205] op_sel_hi:[0,1,1]
	v_cvt_pk_f32_fp8_e32 v[214:215], v26
	v_cvt_pk_f32_fp8_sdwa v[216:217], v26 src0_sel:WORD_1
	v_pk_fma_f32 v[206:207], v[156:157], v[214:215], v[206:207] op_sel_hi:[0,1,1]
	v_pk_fma_f32 v[208:209], v[156:157], v[216:217], v[208:209] op_sel_hi:[0,1,1]
	v_cvt_pk_f32_fp8_e32 v[218:219], v27
	v_cvt_pk_f32_fp8_sdwa v[220:221], v27 src0_sel:WORD_1
	v_pk_fma_f32 v[210:211], v[156:157], v[218:219], v[210:211] op_sel_hi:[0,1,1]
	v_pk_fma_f32 v[212:213], v[156:157], v[220:221], v[212:213] op_sel_hi:[0,1,1]
	s_waitcnt vmcnt(28)
	v_cvt_pk_f32_fp8_e32 v[214:215], v28
	v_cvt_pk_f32_fp8_sdwa v[216:217], v28 src0_sel:WORD_1
	v_pk_fma_f32 v[198:199], v[156:157], v[214:215], v[198:199] op_sel:[1,0,0]
	v_pk_fma_f32 v[200:201], v[156:157], v[216:217], v[200:201] op_sel:[1,0,0]
	v_cvt_pk_f32_fp8_e32 v[218:219], v29
	v_cvt_pk_f32_fp8_sdwa v[220:221], v29 src0_sel:WORD_1
	v_pk_fma_f32 v[202:203], v[156:157], v[218:219], v[202:203] op_sel:[1,0,0]
	v_pk_fma_f32 v[204:205], v[156:157], v[220:221], v[204:205] op_sel:[1,0,0]
	v_cvt_pk_f32_fp8_e32 v[214:215], v30
	v_cvt_pk_f32_fp8_sdwa v[216:217], v30 src0_sel:WORD_1
	v_pk_fma_f32 v[206:207], v[156:157], v[214:215], v[206:207] op_sel:[1,0,0]
	v_pk_fma_f32 v[208:209], v[156:157], v[216:217], v[208:209] op_sel:[1,0,0]
	v_cvt_pk_f32_fp8_e32 v[218:219], v31
	v_cvt_pk_f32_fp8_sdwa v[220:221], v31 src0_sel:WORD_1
	v_pk_fma_f32 v[210:211], v[156:157], v[218:219], v[210:211] op_sel:[1,0,0]
	v_pk_fma_f32 v[212:213], v[156:157], v[220:221], v[212:213] op_sel:[1,0,0]
	ds_read_b128 v[154:157], v139 offset:16
	s_waitcnt vmcnt(27)
	v_cvt_pk_f32_fp8_e32 v[214:215], v32
	v_cvt_pk_f32_fp8_sdwa v[216:217], v32 src0_sel:WORD_1
	v_pk_fma_f32 v[198:199], v[158:159], v[214:215], v[198:199] op_sel_hi:[0,1,1]
	v_pk_fma_f32 v[200:201], v[158:159], v[216:217], v[200:201] op_sel_hi:[0,1,1]
	v_cvt_pk_f32_fp8_e32 v[218:219], v33
	v_cvt_pk_f32_fp8_sdwa v[220:221], v33 src0_sel:WORD_1
	v_pk_fma_f32 v[202:203], v[158:159], v[218:219], v[202:203] op_sel_hi:[0,1,1]
	v_pk_fma_f32 v[204:205], v[158:159], v[220:221], v[204:205] op_sel_hi:[0,1,1]
	v_cvt_pk_f32_fp8_e32 v[214:215], v34
	v_cvt_pk_f32_fp8_sdwa v[216:217], v34 src0_sel:WORD_1
	v_pk_fma_f32 v[206:207], v[158:159], v[214:215], v[206:207] op_sel_hi:[0,1,1]
	v_pk_fma_f32 v[208:209], v[158:159], v[216:217], v[208:209] op_sel_hi:[0,1,1]
	v_cvt_pk_f32_fp8_e32 v[218:219], v35
	v_cvt_pk_f32_fp8_sdwa v[220:221], v35 src0_sel:WORD_1
	v_pk_fma_f32 v[210:211], v[158:159], v[218:219], v[210:211] op_sel_hi:[0,1,1]
	v_pk_fma_f32 v[212:213], v[158:159], v[220:221], v[212:213] op_sel_hi:[0,1,1]
	s_waitcnt vmcnt(26)
	v_cvt_pk_f32_fp8_e32 v[214:215], v36
	v_cvt_pk_f32_fp8_sdwa v[216:217], v36 src0_sel:WORD_1
	v_pk_fma_f32 v[198:199], v[158:159], v[214:215], v[198:199] op_sel:[1,0,0]
	v_pk_fma_f32 v[200:201], v[158:159], v[216:217], v[200:201] op_sel:[1,0,0]
	v_cvt_pk_f32_fp8_e32 v[218:219], v37
	v_cvt_pk_f32_fp8_sdwa v[220:221], v37 src0_sel:WORD_1
	v_pk_fma_f32 v[202:203], v[158:159], v[218:219], v[202:203] op_sel:[1,0,0]
	v_pk_fma_f32 v[204:205], v[158:159], v[220:221], v[204:205] op_sel:[1,0,0]
	v_cvt_pk_f32_fp8_e32 v[214:215], v38
	v_cvt_pk_f32_fp8_sdwa v[216:217], v38 src0_sel:WORD_1
	v_pk_fma_f32 v[206:207], v[158:159], v[214:215], v[206:207] op_sel:[1,0,0]
	v_pk_fma_f32 v[208:209], v[158:159], v[216:217], v[208:209] op_sel:[1,0,0]
	v_cvt_pk_f32_fp8_e32 v[218:219], v39
	v_cvt_pk_f32_fp8_sdwa v[220:221], v39 src0_sel:WORD_1
	v_pk_fma_f32 v[210:211], v[158:159], v[218:219], v[210:211] op_sel:[1,0,0]
	v_pk_fma_f32 v[212:213], v[158:159], v[220:221], v[212:213] op_sel:[1,0,0]
	s_waitcnt lgkmcnt(0)
	v_lshl_add_u32 v154, v154, 8, v138
	v_lshl_add_u32 v155, v155, 8, v138
	v_lshl_add_u32 v156, v156, 8, v138
	v_lshl_add_u32 v157, v157, 8, v138
	buffer_load_dwordx4 v[16:19], v154, s[16:19], s26 offen
	buffer_load_dwordx4 v[20:23], v155, s[16:19], s26 offen
	buffer_load_dwordx4 v[24:27], v156, s[16:19], s26 offen
	buffer_load_dwordx4 v[28:31], v157, s[16:19], s26 offen
	s_waitcnt vmcnt(29)
	v_cvt_pk_f32_fp8_e32 v[214:215], v40
	v_cvt_pk_f32_fp8_sdwa v[216:217], v40 src0_sel:WORD_1
	v_pk_fma_f32 v[198:199], v[160:161], v[214:215], v[198:199] op_sel_hi:[0,1,1]
	v_pk_fma_f32 v[200:201], v[160:161], v[216:217], v[200:201] op_sel_hi:[0,1,1]
	v_cvt_pk_f32_fp8_e32 v[218:219], v41
	v_cvt_pk_f32_fp8_sdwa v[220:221], v41 src0_sel:WORD_1
	v_pk_fma_f32 v[202:203], v[160:161], v[218:219], v[202:203] op_sel_hi:[0,1,1]
	v_pk_fma_f32 v[204:205], v[160:161], v[220:221], v[204:205] op_sel_hi:[0,1,1]
	v_cvt_pk_f32_fp8_e32 v[214:215], v42
	v_cvt_pk_f32_fp8_sdwa v[216:217], v42 src0_sel:WORD_1
	v_pk_fma_f32 v[206:207], v[160:161], v[214:215], v[206:207] op_sel_hi:[0,1,1]
	v_pk_fma_f32 v[208:209], v[160:161], v[216:217], v[208:209] op_sel_hi:[0,1,1]
	v_cvt_pk_f32_fp8_e32 v[218:219], v43
	v_cvt_pk_f32_fp8_sdwa v[220:221], v43 src0_sel:WORD_1
	v_pk_fma_f32 v[210:211], v[160:161], v[218:219], v[210:211] op_sel_hi:[0,1,1]
	v_pk_fma_f32 v[212:213], v[160:161], v[220:221], v[212:213] op_sel_hi:[0,1,1]
	s_waitcnt vmcnt(28)
; #define LAS __attribute__((address_space(3)))
; __device__ __forceinline__ void kv8_issue(u32x4 (&buf)[8], __amdgpu_buffer_rsrc_t rs, int voff  , int sbase  , const int (&iv)[4], int b) {
;     const int jj = b >> 3, l0 = (b & 7) * 8;
;     const int ivb = (jj == 0) ? iv[0] : (jj == 1) ? iv[1] : (jj == 2) ? iv[2] : iv[3];
; #pragma unroll
;     for (int u = 0; u < 8; ++u) { const int si = __builtin_amdgcn_readlane(ivb, l0 + u); buf[u] = __builtin_amdgcn_raw_buffer_load_b128(rs, voff, si * 2048 + sbase, KV8_AUX); }
; }
; __device__ __forceinline__ void kv8_pv(const u32x4 (&buf)[8], f32x2v (&o2)[8], const LAS float* srow, int b) {
;     const LAS f32x4* p4 = (const LAS f32x4*)(srow + b * 8);
;     const f32x4 p0 = p4[0], p1 = p4[1];
;     const float p[8] = {p0.x, p0.y, p0.z, p0.w, p1.x, p1.y, p1.z, p1.w};
; #pragma unroll
;     for (int u = 0; u < 8; ++u) {
;         const u32x4 v = buf[u]; const f32x2v pp = {p[u], p[u]};
;         o2[0] = __builtin_elementwise_fma(pp, __builtin_amdgcn_cvt_pk_f32_fp8(v.x, false), o2[0]); o2[1] = __builtin_elementwise_fma(pp, __builtin_amdgcn_cvt_pk_f32_fp8(v.x, true), o2[1]);
;         o2[2] = __builtin_elementwise_fma(pp, __builtin_amdgcn_cvt_pk_f32_fp8(v.y, false), o2[2]); o2[3] = __builtin_elementwise_fma(pp, __builtin_amdgcn_cvt_pk_f32_fp8(v.y, true), o2[3]);
;         o2[4] = __builtin_elementwise_fma(pp, __builtin_amdgcn_cvt_pk_f32_fp8(v.z, false), o2[4]); o2[5] = __builtin_elementwise_fma(pp, __builtin_amdgcn_cvt_pk_f32_fp8(v.z, true), o2[5]);
;         o2[6] = __builtin_elementwise_fma(pp, __builtin_amdgcn_cvt_pk_f32_fp8(v.w, false), o2[6]); o2[7] = __builtin_elementwise_fma(pp, __builtin_amdgcn_cvt_pk_f32_fp8(v.w, true), o2[7]);
;     }
; }
	v_cvt_pk_f32_fp8_e32 v[214:215], v44
	v_cvt_pk_f32_fp8_sdwa v[216:217], v44 src0_sel:WORD_1
	v_pk_fma_f32 v[198:199], v[160:161], v[214:215], v[198:199] op_sel:[1,0,0]
	v_pk_fma_f32 v[200:201], v[160:161], v[216:217], v[200:201] op_sel:[1,0,0]
	v_cvt_pk_f32_fp8_e32 v[218:219], v45
	v_cvt_pk_f32_fp8_sdwa v[220:221], v45 src0_sel:WORD_1
	v_pk_fma_f32 v[202:203], v[160:161], v[218:219], v[202:203] op_sel:[1,0,0]
	v_pk_fma_f32 v[204:205], v[160:161], v[220:221], v[204:205] op_sel:[1,0,0]
	v_cvt_pk_f32_fp8_e32 v[214:215], v46
	v_cvt_pk_f32_fp8_sdwa v[216:217], v46 src0_sel:WORD_1
	v_pk_fma_f32 v[206:207], v[160:161], v[214:215], v[206:207] op_sel:[1,0,0]
	v_pk_fma_f32 v[208:209], v[160:161], v[216:217], v[208:209] op_sel:[1,0,0]
	v_cvt_pk_f32_fp8_e32 v[218:219], v47
	v_cvt_pk_f32_fp8_sdwa v[220:221], v47 src0_sel:WORD_1
	v_pk_fma_f32 v[210:211], v[160:161], v[218:219], v[210:211] op_sel:[1,0,0]
	v_pk_fma_f32 v[212:213], v[160:161], v[220:221], v[212:213] op_sel:[1,0,0]
	ds_read_b128 v[158:161], v139 offset:32
	s_waitcnt vmcnt(27)
	v_cvt_pk_f32_fp8_e32 v[214:215], v48
	v_cvt_pk_f32_fp8_sdwa v[216:217], v48 src0_sel:WORD_1
	v_pk_fma_f32 v[198:199], v[162:163], v[214:215], v[198:199] op_sel_hi:[0,1,1]
	v_pk_fma_f32 v[200:201], v[162:163], v[216:217], v[200:201] op_sel_hi:[0,1,1]
	v_cvt_pk_f32_fp8_e32 v[218:219], v49
	v_cvt_pk_f32_fp8_sdwa v[220:221], v49 src0_sel:WORD_1
	v_pk_fma_f32 v[202:203], v[162:163], v[218:219], v[202:203] op_sel_hi:[0,1,1]
	v_pk_fma_f32 v[204:205], v[162:163], v[220:221], v[204:205] op_sel_hi:[0,1,1]
	v_cvt_pk_f32_fp8_e32 v[214:215], v50
	v_cvt_pk_f32_fp8_sdwa v[216:217], v50 src0_sel:WORD_1
	v_pk_fma_f32 v[206:207], v[162:163], v[214:215], v[206:207] op_sel_hi:[0,1,1]
	v_pk_fma_f32 v[208:209], v[162:163], v[216:217], v[208:209] op_sel_hi:[0,1,1]
	v_cvt_pk_f32_fp8_e32 v[218:219], v51
	v_cvt_pk_f32_fp8_sdwa v[220:221], v51 src0_sel:WORD_1
	v_pk_fma_f32 v[210:211], v[162:163], v[218:219], v[210:211] op_sel_hi:[0,1,1]
	v_pk_fma_f32 v[212:213], v[162:163], v[220:221], v[212:213] op_sel_hi:[0,1,1]
	s_waitcnt vmcnt(26)
	v_cvt_pk_f32_fp8_e32 v[214:215], v52
	v_cvt_pk_f32_fp8_sdwa v[216:217], v52 src0_sel:WORD_1
	v_pk_fma_f32 v[198:199], v[162:163], v[214:215], v[198:199] op_sel:[1,0,0]
	v_pk_fma_f32 v[200:201], v[162:163], v[216:217], v[200:201] op_sel:[1,0,0]
	v_cvt_pk_f32_fp8_e32 v[218:219], v53
	v_cvt_pk_f32_fp8_sdwa v[220:221], v53 src0_sel:WORD_1
	v_pk_fma_f32 v[202:203], v[162:163], v[218:219], v[202:203] op_sel:[1,0,0]
	v_pk_fma_f32 v[204:205], v[162:163], v[220:221], v[204:205] op_sel:[1,0,0]
	v_cvt_pk_f32_fp8_e32 v[214:215], v54
	v_cvt_pk_f32_fp8_sdwa v[216:217], v54 src0_sel:WORD_1
	v_pk_fma_f32 v[206:207], v[162:163], v[214:215], v[206:207] op_sel:[1,0,0]
	v_pk_fma_f32 v[208:209], v[162:163], v[216:217], v[208:209] op_sel:[1,0,0]
	v_cvt_pk_f32_fp8_e32 v[218:219], v55
	v_cvt_pk_f32_fp8_sdwa v[220:221], v55 src0_sel:WORD_1
	v_pk_fma_f32 v[210:211], v[162:163], v[218:219], v[210:211] op_sel:[1,0,0]
	v_pk_fma_f32 v[212:213], v[162:163], v[220:221], v[212:213] op_sel:[1,0,0]
	s_waitcnt lgkmcnt(0)
	v_lshl_add_u32 v158, v158, 8, v138
	v_lshl_add_u32 v159, v159, 8, v138
	v_lshl_add_u32 v160, v160, 8, v138
	v_lshl_add_u32 v161, v161, 8, v138
	buffer_load_dwordx4 v[32:35], v158, s[16:19], s26 offen
	buffer_load_dwordx4 v[36:39], v159, s[16:19], s26 offen
	buffer_load_dwordx4 v[40:43], v160, s[16:19], s26 offen
	buffer_load_dwordx4 v[44:47], v161, s[16:19], s26 offen
	s_waitcnt vmcnt(29)
	v_cvt_pk_f32_fp8_e32 v[214:215], v56
	v_cvt_pk_f32_fp8_sdwa v[216:217], v56 src0_sel:WORD_1
	v_pk_fma_f32 v[198:199], v[164:165], v[214:215], v[198:199] op_sel_hi:[0,1,1]
	v_pk_fma_f32 v[200:201], v[164:165], v[216:217], v[200:201] op_sel_hi:[0,1,1]
	v_cvt_pk_f32_fp8_e32 v[218:219], v57
	v_cvt_pk_f32_fp8_sdwa v[220:221], v57 src0_sel:WORD_1
	v_pk_fma_f32 v[202:203], v[164:165], v[218:219], v[202:203] op_sel_hi:[0,1,1]
	v_pk_fma_f32 v[204:205], v[164:165], v[220:221], v[204:205] op_sel_hi:[0,1,1]
	v_cvt_pk_f32_fp8_e32 v[214:215], v58
	v_cvt_pk_f32_fp8_sdwa v[216:217], v58 src0_sel:WORD_1
	v_pk_fma_f32 v[206:207], v[164:165], v[214:215], v[206:207] op_sel_hi:[0,1,1]
	v_pk_fma_f32 v[208:209], v[164:165], v[216:217], v[208:209] op_sel_hi:[0,1,1]
	v_cvt_pk_f32_fp8_e32 v[218:219], v59
	v_cvt_pk_f32_fp8_sdwa v[220:221], v59 src0_sel:WORD_1
	v_pk_fma_f32 v[210:211], v[164:165], v[218:219], v[210:211] op_sel_hi:[0,1,1]
	v_pk_fma_f32 v[212:213], v[164:165], v[220:221], v[212:213] op_sel_hi:[0,1,1]
	s_waitcnt vmcnt(28)
	v_cvt_pk_f32_fp8_e32 v[214:215], v60
	v_cvt_pk_f32_fp8_sdwa v[216:217], v60 src0_sel:WORD_1
	v_pk_fma_f32 v[198:199], v[164:165], v[214:215], v[198:199] op_sel:[1,0,0]
	v_pk_fma_f32 v[200:201], v[164:165], v[216:217], v[200:201] op_sel:[1,0,0]
	v_cvt_pk_f32_fp8_e32 v[218:219], v61
	v_cvt_pk_f32_fp8_sdwa v[220:221], v61 src0_sel:WORD_1
	v_pk_fma_f32 v[202:203], v[164:165], v[218:219], v[202:203] op_sel:[1,0,0]
	v_pk_fma_f32 v[204:205], v[164:165], v[220:221], v[204:205] op_sel:[1,0,0]
	v_cvt_pk_f32_fp8_e32 v[214:215], v62
	v_cvt_pk_f32_fp8_sdwa v[216:217], v62 src0_sel:WORD_1
	v_pk_fma_f32 v[206:207], v[164:165], v[214:215], v[206:207] op_sel:[1,0,0]
	v_pk_fma_f32 v[208:209], v[164:165], v[216:217], v[208:209] op_sel:[1,0,0]
	v_cvt_pk_f32_fp8_e32 v[218:219], v63
	v_cvt_pk_f32_fp8_sdwa v[220:221], v63 src0_sel:WORD_1
	v_pk_fma_f32 v[210:211], v[164:165], v[218:219], v[210:211] op_sel:[1,0,0]
	v_pk_fma_f32 v[212:213], v[164:165], v[220:221], v[212:213] op_sel:[1,0,0]
	ds_read_b128 v[162:165], v139 offset:48
	s_waitcnt vmcnt(27)
; #define LAS __attribute__((address_space(3)))
; __device__ __forceinline__ void kv8_issue(u32x4 (&buf)[8], __amdgpu_buffer_rsrc_t rs, int voff  , int sbase  , const int (&iv)[4], int b) {
;     const int jj = b >> 3, l0 = (b & 7) * 8;
;     const int ivb = (jj == 0) ? iv[0] : (jj == 1) ? iv[1] : (jj == 2) ? iv[2] : iv[3];
; #pragma unroll
;     for (int u = 0; u < 8; ++u) { const int si = __builtin_amdgcn_readlane(ivb, l0 + u); buf[u] = __builtin_amdgcn_raw_buffer_load_b128(rs, voff, si * 2048 + sbase, KV8_AUX); }
; }
; __device__ __forceinline__ void kv8_pv(const u32x4 (&buf)[8], f32x2v (&o2)[8], const LAS float* srow, int b) {
;     const LAS f32x4* p4 = (const LAS f32x4*)(srow + b * 8);
;     const f32x4 p0 = p4[0], p1 = p4[1];
;     const float p[8] = {p0.x, p0.y, p0.z, p0.w, p1.x, p1.y, p1.z, p1.w};
; #pragma unroll
;     for (int u = 0; u < 8; ++u) {
;         const u32x4 v = buf[u]; const f32x2v pp = {p[u], p[u]};
;         o2[0] = __builtin_elementwise_fma(pp, __builtin_amdgcn_cvt_pk_f32_fp8(v.x, false), o2[0]); o2[1] = __builtin_elementwise_fma(pp, __builtin_amdgcn_cvt_pk_f32_fp8(v.x, true), o2[1]);
;         o2[2] = __builtin_elementwise_fma(pp, __builtin_amdgcn_cvt_pk_f32_fp8(v.y, false), o2[2]); o2[3] = __builtin_elementwise_fma(pp, __builtin_amdgcn_cvt_pk_f32_fp8(v.y, true), o2[3]);
;         o2[4] = __builtin_elementwise_fma(pp, __builtin_amdgcn_cvt_pk_f32_fp8(v.z, false), o2[4]); o2[5] = __builtin_elementwise_fma(pp, __builtin_amdgcn_cvt_pk_f32_fp8(v.z, true), o2[5]);
;         o2[6] = __builtin_elementwise_fma(pp, __builtin_amdgcn_cvt_pk_f32_fp8(v.w, false), o2[6]); o2[7] = __builtin_elementwise_fma(pp, __builtin_amdgcn_cvt_pk_f32_fp8(v.w, true), o2[7]);
;     }
; }
	v_cvt_pk_f32_fp8_e32 v[214:215], v64
	v_cvt_pk_f32_fp8_sdwa v[216:217], v64 src0_sel:WORD_1
	v_pk_fma_f32 v[198:199], v[166:167], v[214:215], v[198:199] op_sel_hi:[0,1,1]
	v_pk_fma_f32 v[200:201], v[166:167], v[216:217], v[200:201] op_sel_hi:[0,1,1]
	v_cvt_pk_f32_fp8_e32 v[218:219], v65
	v_cvt_pk_f32_fp8_sdwa v[220:221], v65 src0_sel:WORD_1
	v_pk_fma_f32 v[202:203], v[166:167], v[218:219], v[202:203] op_sel_hi:[0,1,1]
	v_pk_fma_f32 v[204:205], v[166:167], v[220:221], v[204:205] op_sel_hi:[0,1,1]
	v_cvt_pk_f32_fp8_e32 v[214:215], v66
	v_cvt_pk_f32_fp8_sdwa v[216:217], v66 src0_sel:WORD_1
	v_pk_fma_f32 v[206:207], v[166:167], v[214:215], v[206:207] op_sel_hi:[0,1,1]
	v_pk_fma_f32 v[208:209], v[166:167], v[216:217], v[208:209] op_sel_hi:[0,1,1]
	v_cvt_pk_f32_fp8_e32 v[218:219], v67
	v_cvt_pk_f32_fp8_sdwa v[220:221], v67 src0_sel:WORD_1
	v_pk_fma_f32 v[210:211], v[166:167], v[218:219], v[210:211] op_sel_hi:[0,1,1]
	v_pk_fma_f32 v[212:213], v[166:167], v[220:221], v[212:213] op_sel_hi:[0,1,1]
	s_waitcnt vmcnt(26)
	v_cvt_pk_f32_fp8_e32 v[214:215], v68
	v_cvt_pk_f32_fp8_sdwa v[216:217], v68 src0_sel:WORD_1
	v_pk_fma_f32 v[198:199], v[166:167], v[214:215], v[198:199] op_sel:[1,0,0]
	v_pk_fma_f32 v[200:201], v[166:167], v[216:217], v[200:201] op_sel:[1,0,0]
	v_cvt_pk_f32_fp8_e32 v[218:219], v69
	v_cvt_pk_f32_fp8_sdwa v[220:221], v69 src0_sel:WORD_1
	v_pk_fma_f32 v[202:203], v[166:167], v[218:219], v[202:203] op_sel:[1,0,0]
	v_pk_fma_f32 v[204:205], v[166:167], v[220:221], v[204:205] op_sel:[1,0,0]
	v_cvt_pk_f32_fp8_e32 v[214:215], v70
	v_cvt_pk_f32_fp8_sdwa v[216:217], v70 src0_sel:WORD_1
	v_pk_fma_f32 v[206:207], v[166:167], v[214:215], v[206:207] op_sel:[1,0,0]
	v_pk_fma_f32 v[208:209], v[166:167], v[216:217], v[208:209] op_sel:[1,0,0]
	v_cvt_pk_f32_fp8_e32 v[218:219], v71
	v_cvt_pk_f32_fp8_sdwa v[220:221], v71 src0_sel:WORD_1
	v_pk_fma_f32 v[210:211], v[166:167], v[218:219], v[210:211] op_sel:[1,0,0]
	v_pk_fma_f32 v[212:213], v[166:167], v[220:221], v[212:213] op_sel:[1,0,0]
	s_waitcnt lgkmcnt(0)
	v_lshl_add_u32 v162, v162, 8, v138
	v_lshl_add_u32 v163, v163, 8, v138
	v_lshl_add_u32 v164, v164, 8, v138
	v_lshl_add_u32 v165, v165, 8, v138
	buffer_load_dwordx4 v[48:51], v162, s[16:19], s26 offen
	buffer_load_dwordx4 v[52:55], v163, s[16:19], s26 offen
	buffer_load_dwordx4 v[56:59], v164, s[16:19], s26 offen
	buffer_load_dwordx4 v[60:63], v165, s[16:19], s26 offen
	s_waitcnt vmcnt(29)
	v_cvt_pk_f32_fp8_e32 v[214:215], v72
	v_cvt_pk_f32_fp8_sdwa v[216:217], v72 src0_sel:WORD_1
	v_pk_fma_f32 v[198:199], v[168:169], v[214:215], v[198:199] op_sel_hi:[0,1,1]
	v_pk_fma_f32 v[200:201], v[168:169], v[216:217], v[200:201] op_sel_hi:[0,1,1]
	v_cvt_pk_f32_fp8_e32 v[218:219], v73
	v_cvt_pk_f32_fp8_sdwa v[220:221], v73 src0_sel:WORD_1
	v_pk_fma_f32 v[202:203], v[168:169], v[218:219], v[202:203] op_sel_hi:[0,1,1]
	v_pk_fma_f32 v[204:205], v[168:169], v[220:221], v[204:205] op_sel_hi:[0,1,1]
	v_cvt_pk_f32_fp8_e32 v[214:215], v74
	v_cvt_pk_f32_fp8_sdwa v[216:217], v74 src0_sel:WORD_1
	v_pk_fma_f32 v[206:207], v[168:169], v[214:215], v[206:207] op_sel_hi:[0,1,1]
	v_pk_fma_f32 v[208:209], v[168:169], v[216:217], v[208:209] op_sel_hi:[0,1,1]
	v_cvt_pk_f32_fp8_e32 v[218:219], v75
	v_cvt_pk_f32_fp8_sdwa v[220:221], v75 src0_sel:WORD_1
	v_pk_fma_f32 v[210:211], v[168:169], v[218:219], v[210:211] op_sel_hi:[0,1,1]
	v_pk_fma_f32 v[212:213], v[168:169], v[220:221], v[212:213] op_sel_hi:[0,1,1]
	s_waitcnt vmcnt(28)
	v_cvt_pk_f32_fp8_e32 v[214:215], v76
	v_cvt_pk_f32_fp8_sdwa v[216:217], v76 src0_sel:WORD_1
	v_pk_fma_f32 v[198:199], v[168:169], v[214:215], v[198:199] op_sel:[1,0,0]
	v_pk_fma_f32 v[200:201], v[168:169], v[216:217], v[200:201] op_sel:[1,0,0]
	v_cvt_pk_f32_fp8_e32 v[218:219], v77
	v_cvt_pk_f32_fp8_sdwa v[220:221], v77 src0_sel:WORD_1
	v_pk_fma_f32 v[202:203], v[168:169], v[218:219], v[202:203] op_sel:[1,0,0]
	v_pk_fma_f32 v[204:205], v[168:169], v[220:221], v[204:205] op_sel:[1,0,0]
	v_cvt_pk_f32_fp8_e32 v[214:215], v78
	v_cvt_pk_f32_fp8_sdwa v[216:217], v78 src0_sel:WORD_1
	v_pk_fma_f32 v[206:207], v[168:169], v[214:215], v[206:207] op_sel:[1,0,0]
	v_pk_fma_f32 v[208:209], v[168:169], v[216:217], v[208:209] op_sel:[1,0,0]
	v_cvt_pk_f32_fp8_e32 v[218:219], v79
	v_cvt_pk_f32_fp8_sdwa v[220:221], v79 src0_sel:WORD_1
	v_pk_fma_f32 v[210:211], v[168:169], v[218:219], v[210:211] op_sel:[1,0,0]
	v_pk_fma_f32 v[212:213], v[168:169], v[220:221], v[212:213] op_sel:[1,0,0]
	ds_read_b128 v[166:169], v139 offset:64
	s_waitcnt vmcnt(27)
	v_cvt_pk_f32_fp8_e32 v[214:215], v80
	v_cvt_pk_f32_fp8_sdwa v[216:217], v80 src0_sel:WORD_1
	v_pk_fma_f32 v[198:199], v[170:171], v[214:215], v[198:199] op_sel_hi:[0,1,1]
	v_pk_fma_f32 v[200:201], v[170:171], v[216:217], v[200:201] op_sel_hi:[0,1,1]
	v_cvt_pk_f32_fp8_e32 v[218:219], v81
	v_cvt_pk_f32_fp8_sdwa v[220:221], v81 src0_sel:WORD_1
	v_pk_fma_f32 v[202:203], v[170:171], v[218:219], v[202:203] op_sel_hi:[0,1,1]
	v_pk_fma_f32 v[204:205], v[170:171], v[220:221], v[204:205] op_sel_hi:[0,1,1]
	v_cvt_pk_f32_fp8_e32 v[214:215], v82
	v_cvt_pk_f32_fp8_sdwa v[216:217], v82 src0_sel:WORD_1
	v_pk_fma_f32 v[206:207], v[170:171], v[214:215], v[206:207] op_sel_hi:[0,1,1]
	v_pk_fma_f32 v[208:209], v[170:171], v[216:217], v[208:209] op_sel_hi:[0,1,1]
	v_cvt_pk_f32_fp8_e32 v[218:219], v83
	v_cvt_pk_f32_fp8_sdwa v[220:221], v83 src0_sel:WORD_1
	v_pk_fma_f32 v[210:211], v[170:171], v[218:219], v[210:211] op_sel_hi:[0,1,1]
	v_pk_fma_f32 v[212:213], v[170:171], v[220:221], v[212:213] op_sel_hi:[0,1,1]
	s_waitcnt vmcnt(26)
; #define LAS __attribute__((address_space(3)))
; __device__ __forceinline__ void kv8_issue(u32x4 (&buf)[8], __amdgpu_buffer_rsrc_t rs, int voff  , int sbase  , const int (&iv)[4], int b) {
;     const int jj = b >> 3, l0 = (b & 7) * 8;
;     const int ivb = (jj == 0) ? iv[0] : (jj == 1) ? iv[1] : (jj == 2) ? iv[2] : iv[3];
; #pragma unroll
;     for (int u = 0; u < 8; ++u) { const int si = __builtin_amdgcn_readlane(ivb, l0 + u); buf[u] = __builtin_amdgcn_raw_buffer_load_b128(rs, voff, si * 2048 + sbase, KV8_AUX); }
; }
; __device__ __forceinline__ void kv8_pv(const u32x4 (&buf)[8], f32x2v (&o2)[8], const LAS float* srow, int b) {
;     const LAS f32x4* p4 = (const LAS f32x4*)(srow + b * 8);
;     const f32x4 p0 = p4[0], p1 = p4[1];
;     const float p[8] = {p0.x, p0.y, p0.z, p0.w, p1.x, p1.y, p1.z, p1.w};
; #pragma unroll
;     for (int u = 0; u < 8; ++u) {
;         const u32x4 v = buf[u]; const f32x2v pp = {p[u], p[u]};
;         o2[0] = __builtin_elementwise_fma(pp, __builtin_amdgcn_cvt_pk_f32_fp8(v.x, false), o2[0]); o2[1] = __builtin_elementwise_fma(pp, __builtin_amdgcn_cvt_pk_f32_fp8(v.x, true), o2[1]);
;         o2[2] = __builtin_elementwise_fma(pp, __builtin_amdgcn_cvt_pk_f32_fp8(v.y, false), o2[2]); o2[3] = __builtin_elementwise_fma(pp, __builtin_amdgcn_cvt_pk_f32_fp8(v.y, true), o2[3]);
;         o2[4] = __builtin_elementwise_fma(pp, __builtin_amdgcn_cvt_pk_f32_fp8(v.z, false), o2[4]); o2[5] = __builtin_elementwise_fma(pp, __builtin_amdgcn_cvt_pk_f32_fp8(v.z, true), o2[5]);
;         o2[6] = __builtin_elementwise_fma(pp, __builtin_amdgcn_cvt_pk_f32_fp8(v.w, false), o2[6]); o2[7] = __builtin_elementwise_fma(pp, __builtin_amdgcn_cvt_pk_f32_fp8(v.w, true), o2[7]);
;     }
; }
	v_cvt_pk_f32_fp8_e32 v[214:215], v84
	v_cvt_pk_f32_fp8_sdwa v[216:217], v84 src0_sel:WORD_1
	v_pk_fma_f32 v[198:199], v[170:171], v[214:215], v[198:199] op_sel:[1,0,0]
	v_pk_fma_f32 v[200:201], v[170:171], v[216:217], v[200:201] op_sel:[1,0,0]
	v_cvt_pk_f32_fp8_e32 v[218:219], v85
	v_cvt_pk_f32_fp8_sdwa v[220:221], v85 src0_sel:WORD_1
	v_pk_fma_f32 v[202:203], v[170:171], v[218:219], v[202:203] op_sel:[1,0,0]
	v_pk_fma_f32 v[204:205], v[170:171], v[220:221], v[204:205] op_sel:[1,0,0]
	v_cvt_pk_f32_fp8_e32 v[214:215], v86
	v_cvt_pk_f32_fp8_sdwa v[216:217], v86 src0_sel:WORD_1
	v_pk_fma_f32 v[206:207], v[170:171], v[214:215], v[206:207] op_sel:[1,0,0]
	v_pk_fma_f32 v[208:209], v[170:171], v[216:217], v[208:209] op_sel:[1,0,0]
	v_cvt_pk_f32_fp8_e32 v[218:219], v87
	v_cvt_pk_f32_fp8_sdwa v[220:221], v87 src0_sel:WORD_1
	v_pk_fma_f32 v[210:211], v[170:171], v[218:219], v[210:211] op_sel:[1,0,0]
	v_pk_fma_f32 v[212:213], v[170:171], v[220:221], v[212:213] op_sel:[1,0,0]
	s_waitcnt lgkmcnt(0)
	v_lshl_add_u32 v166, v166, 8, v138
	v_lshl_add_u32 v167, v167, 8, v138
	v_lshl_add_u32 v168, v168, 8, v138
	v_lshl_add_u32 v169, v169, 8, v138
	buffer_load_dwordx4 v[64:67], v166, s[16:19], s26 offen
	buffer_load_dwordx4 v[68:71], v167, s[16:19], s26 offen
	buffer_load_dwordx4 v[72:75], v168, s[16:19], s26 offen
	buffer_load_dwordx4 v[76:79], v169, s[16:19], s26 offen
	s_waitcnt vmcnt(29)
	v_cvt_pk_f32_fp8_e32 v[214:215], v88
	v_cvt_pk_f32_fp8_sdwa v[216:217], v88 src0_sel:WORD_1
	v_pk_fma_f32 v[198:199], v[172:173], v[214:215], v[198:199] op_sel_hi:[0,1,1]
	v_pk_fma_f32 v[200:201], v[172:173], v[216:217], v[200:201] op_sel_hi:[0,1,1]
	v_cvt_pk_f32_fp8_e32 v[218:219], v89
	v_cvt_pk_f32_fp8_sdwa v[220:221], v89 src0_sel:WORD_1
	v_pk_fma_f32 v[202:203], v[172:173], v[218:219], v[202:203] op_sel_hi:[0,1,1]
	v_pk_fma_f32 v[204:205], v[172:173], v[220:221], v[204:205] op_sel_hi:[0,1,1]
	v_cvt_pk_f32_fp8_e32 v[214:215], v90
	v_cvt_pk_f32_fp8_sdwa v[216:217], v90 src0_sel:WORD_1
	v_pk_fma_f32 v[206:207], v[172:173], v[214:215], v[206:207] op_sel_hi:[0,1,1]
	v_pk_fma_f32 v[208:209], v[172:173], v[216:217], v[208:209] op_sel_hi:[0,1,1]
	v_cvt_pk_f32_fp8_e32 v[218:219], v91
	v_cvt_pk_f32_fp8_sdwa v[220:221], v91 src0_sel:WORD_1
	v_pk_fma_f32 v[210:211], v[172:173], v[218:219], v[210:211] op_sel_hi:[0,1,1]
	v_pk_fma_f32 v[212:213], v[172:173], v[220:221], v[212:213] op_sel_hi:[0,1,1]
	s_waitcnt vmcnt(28)
	v_cvt_pk_f32_fp8_e32 v[214:215], v92
	v_cvt_pk_f32_fp8_sdwa v[216:217], v92 src0_sel:WORD_1
	v_pk_fma_f32 v[198:199], v[172:173], v[214:215], v[198:199] op_sel:[1,0,0]
	v_pk_fma_f32 v[200:201], v[172:173], v[216:217], v[200:201] op_sel:[1,0,0]
	v_cvt_pk_f32_fp8_e32 v[218:219], v93
	v_cvt_pk_f32_fp8_sdwa v[220:221], v93 src0_sel:WORD_1
	v_pk_fma_f32 v[202:203], v[172:173], v[218:219], v[202:203] op_sel:[1,0,0]
	v_pk_fma_f32 v[204:205], v[172:173], v[220:221], v[204:205] op_sel:[1,0,0]
	v_cvt_pk_f32_fp8_e32 v[214:215], v94
	v_cvt_pk_f32_fp8_sdwa v[216:217], v94 src0_sel:WORD_1
	v_pk_fma_f32 v[206:207], v[172:173], v[214:215], v[206:207] op_sel:[1,0,0]
	v_pk_fma_f32 v[208:209], v[172:173], v[216:217], v[208:209] op_sel:[1,0,0]
	v_cvt_pk_f32_fp8_e32 v[218:219], v95
	v_cvt_pk_f32_fp8_sdwa v[220:221], v95 src0_sel:WORD_1
	v_pk_fma_f32 v[210:211], v[172:173], v[218:219], v[210:211] op_sel:[1,0,0]
	v_pk_fma_f32 v[212:213], v[172:173], v[220:221], v[212:213] op_sel:[1,0,0]
	ds_read_b128 v[170:173], v139 offset:80
	s_waitcnt vmcnt(27)
	v_cvt_pk_f32_fp8_e32 v[214:215], v96
	v_cvt_pk_f32_fp8_sdwa v[216:217], v96 src0_sel:WORD_1
	v_pk_fma_f32 v[198:199], v[174:175], v[214:215], v[198:199] op_sel_hi:[0,1,1]
	v_pk_fma_f32 v[200:201], v[174:175], v[216:217], v[200:201] op_sel_hi:[0,1,1]
	v_cvt_pk_f32_fp8_e32 v[218:219], v97
	v_cvt_pk_f32_fp8_sdwa v[220:221], v97 src0_sel:WORD_1
	v_pk_fma_f32 v[202:203], v[174:175], v[218:219], v[202:203] op_sel_hi:[0,1,1]
	v_pk_fma_f32 v[204:205], v[174:175], v[220:221], v[204:205] op_sel_hi:[0,1,1]
	v_cvt_pk_f32_fp8_e32 v[214:215], v98
	v_cvt_pk_f32_fp8_sdwa v[216:217], v98 src0_sel:WORD_1
	v_pk_fma_f32 v[206:207], v[174:175], v[214:215], v[206:207] op_sel_hi:[0,1,1]
	v_pk_fma_f32 v[208:209], v[174:175], v[216:217], v[208:209] op_sel_hi:[0,1,1]
	v_cvt_pk_f32_fp8_e32 v[218:219], v99
	v_cvt_pk_f32_fp8_sdwa v[220:221], v99 src0_sel:WORD_1
	v_pk_fma_f32 v[210:211], v[174:175], v[218:219], v[210:211] op_sel_hi:[0,1,1]
	v_pk_fma_f32 v[212:213], v[174:175], v[220:221], v[212:213] op_sel_hi:[0,1,1]
	s_waitcnt vmcnt(26)
	v_cvt_pk_f32_fp8_e32 v[214:215], v100
	v_cvt_pk_f32_fp8_sdwa v[216:217], v100 src0_sel:WORD_1
	v_pk_fma_f32 v[198:199], v[174:175], v[214:215], v[198:199] op_sel:[1,0,0]
	v_pk_fma_f32 v[200:201], v[174:175], v[216:217], v[200:201] op_sel:[1,0,0]
	v_cvt_pk_f32_fp8_e32 v[218:219], v101
	v_cvt_pk_f32_fp8_sdwa v[220:221], v101 src0_sel:WORD_1
	v_pk_fma_f32 v[202:203], v[174:175], v[218:219], v[202:203] op_sel:[1,0,0]
	v_pk_fma_f32 v[204:205], v[174:175], v[220:221], v[204:205] op_sel:[1,0,0]
	v_cvt_pk_f32_fp8_e32 v[214:215], v102
	v_cvt_pk_f32_fp8_sdwa v[216:217], v102 src0_sel:WORD_1
	v_pk_fma_f32 v[206:207], v[174:175], v[214:215], v[206:207] op_sel:[1,0,0]
	v_pk_fma_f32 v[208:209], v[174:175], v[216:217], v[208:209] op_sel:[1,0,0]
	v_cvt_pk_f32_fp8_e32 v[218:219], v103
	v_cvt_pk_f32_fp8_sdwa v[220:221], v103 src0_sel:WORD_1
	v_pk_fma_f32 v[210:211], v[174:175], v[218:219], v[210:211] op_sel:[1,0,0]
	v_pk_fma_f32 v[212:213], v[174:175], v[220:221], v[212:213] op_sel:[1,0,0]
	s_waitcnt lgkmcnt(0)
; #define LAS __attribute__((address_space(3)))
; __device__ __forceinline__ void kv8_issue(u32x4 (&buf)[8], __amdgpu_buffer_rsrc_t rs, int voff  , int sbase  , const int (&iv)[4], int b) {
;     const int jj = b >> 3, l0 = (b & 7) * 8;
;     const int ivb = (jj == 0) ? iv[0] : (jj == 1) ? iv[1] : (jj == 2) ? iv[2] : iv[3];
; #pragma unroll
;     for (int u = 0; u < 8; ++u) { const int si = __builtin_amdgcn_readlane(ivb, l0 + u); buf[u] = __builtin_amdgcn_raw_buffer_load_b128(rs, voff, si * 2048 + sbase, KV8_AUX); }
; }
; __device__ __forceinline__ void kv8_pv(const u32x4 (&buf)[8], f32x2v (&o2)[8], const LAS float* srow, int b) {
;     const LAS f32x4* p4 = (const LAS f32x4*)(srow + b * 8);
;     const f32x4 p0 = p4[0], p1 = p4[1];
;     const float p[8] = {p0.x, p0.y, p0.z, p0.w, p1.x, p1.y, p1.z, p1.w};
; #pragma unroll
;     for (int u = 0; u < 8; ++u) {
;         const u32x4 v = buf[u]; const f32x2v pp = {p[u], p[u]};
;         o2[0] = __builtin_elementwise_fma(pp, __builtin_amdgcn_cvt_pk_f32_fp8(v.x, false), o2[0]); o2[1] = __builtin_elementwise_fma(pp, __builtin_amdgcn_cvt_pk_f32_fp8(v.x, true), o2[1]);
;         o2[2] = __builtin_elementwise_fma(pp, __builtin_amdgcn_cvt_pk_f32_fp8(v.y, false), o2[2]); o2[3] = __builtin_elementwise_fma(pp, __builtin_amdgcn_cvt_pk_f32_fp8(v.y, true), o2[3]);
;         o2[4] = __builtin_elementwise_fma(pp, __builtin_amdgcn_cvt_pk_f32_fp8(v.z, false), o2[4]); o2[5] = __builtin_elementwise_fma(pp, __builtin_amdgcn_cvt_pk_f32_fp8(v.z, true), o2[5]);
;         o2[6] = __builtin_elementwise_fma(pp, __builtin_amdgcn_cvt_pk_f32_fp8(v.w, false), o2[6]); o2[7] = __builtin_elementwise_fma(pp, __builtin_amdgcn_cvt_pk_f32_fp8(v.w, true), o2[7]);
;     }
; }
	v_lshl_add_u32 v170, v170, 8, v138
	v_lshl_add_u32 v171, v171, 8, v138
	v_lshl_add_u32 v172, v172, 8, v138
	v_lshl_add_u32 v173, v173, 8, v138
	buffer_load_dwordx4 v[80:83], v170, s[16:19], s26 offen
	buffer_load_dwordx4 v[84:87], v171, s[16:19], s26 offen
	buffer_load_dwordx4 v[88:91], v172, s[16:19], s26 offen
	buffer_load_dwordx4 v[92:95], v173, s[16:19], s26 offen
	s_waitcnt vmcnt(29)
	v_cvt_pk_f32_fp8_e32 v[214:215], v104
	v_cvt_pk_f32_fp8_sdwa v[216:217], v104 src0_sel:WORD_1
	v_pk_fma_f32 v[198:199], v[176:177], v[214:215], v[198:199] op_sel_hi:[0,1,1]
	v_pk_fma_f32 v[200:201], v[176:177], v[216:217], v[200:201] op_sel_hi:[0,1,1]
	v_cvt_pk_f32_fp8_e32 v[218:219], v105
	v_cvt_pk_f32_fp8_sdwa v[220:221], v105 src0_sel:WORD_1
	v_pk_fma_f32 v[202:203], v[176:177], v[218:219], v[202:203] op_sel_hi:[0,1,1]
	v_pk_fma_f32 v[204:205], v[176:177], v[220:221], v[204:205] op_sel_hi:[0,1,1]
	v_cvt_pk_f32_fp8_e32 v[214:215], v106
	v_cvt_pk_f32_fp8_sdwa v[216:217], v106 src0_sel:WORD_1
	v_pk_fma_f32 v[206:207], v[176:177], v[214:215], v[206:207] op_sel_hi:[0,1,1]
	v_pk_fma_f32 v[208:209], v[176:177], v[216:217], v[208:209] op_sel_hi:[0,1,1]
	v_cvt_pk_f32_fp8_e32 v[218:219], v107
	v_cvt_pk_f32_fp8_sdwa v[220:221], v107 src0_sel:WORD_1
	v_pk_fma_f32 v[210:211], v[176:177], v[218:219], v[210:211] op_sel_hi:[0,1,1]
	v_pk_fma_f32 v[212:213], v[176:177], v[220:221], v[212:213] op_sel_hi:[0,1,1]
	s_waitcnt vmcnt(28)
	v_cvt_pk_f32_fp8_e32 v[214:215], v108
	v_cvt_pk_f32_fp8_sdwa v[216:217], v108 src0_sel:WORD_1
	v_pk_fma_f32 v[198:199], v[176:177], v[214:215], v[198:199] op_sel:[1,0,0]
	v_pk_fma_f32 v[200:201], v[176:177], v[216:217], v[200:201] op_sel:[1,0,0]
	v_cvt_pk_f32_fp8_e32 v[218:219], v109
	v_cvt_pk_f32_fp8_sdwa v[220:221], v109 src0_sel:WORD_1
	v_pk_fma_f32 v[202:203], v[176:177], v[218:219], v[202:203] op_sel:[1,0,0]
	v_pk_fma_f32 v[204:205], v[176:177], v[220:221], v[204:205] op_sel:[1,0,0]
	v_cvt_pk_f32_fp8_e32 v[214:215], v110
	v_cvt_pk_f32_fp8_sdwa v[216:217], v110 src0_sel:WORD_1
	v_pk_fma_f32 v[206:207], v[176:177], v[214:215], v[206:207] op_sel:[1,0,0]
	v_pk_fma_f32 v[208:209], v[176:177], v[216:217], v[208:209] op_sel:[1,0,0]
	v_cvt_pk_f32_fp8_e32 v[218:219], v111
	v_cvt_pk_f32_fp8_sdwa v[220:221], v111 src0_sel:WORD_1
	v_pk_fma_f32 v[210:211], v[176:177], v[218:219], v[210:211] op_sel:[1,0,0]
	v_pk_fma_f32 v[212:213], v[176:177], v[220:221], v[212:213] op_sel:[1,0,0]
	ds_read_b128 v[174:177], v139 offset:96
	s_waitcnt vmcnt(27)
	v_cvt_pk_f32_fp8_e32 v[214:215], v112
	v_cvt_pk_f32_fp8_sdwa v[216:217], v112 src0_sel:WORD_1
	v_pk_fma_f32 v[198:199], v[178:179], v[214:215], v[198:199] op_sel_hi:[0,1,1]
	v_pk_fma_f32 v[200:201], v[178:179], v[216:217], v[200:201] op_sel_hi:[0,1,1]
	v_cvt_pk_f32_fp8_e32 v[218:219], v113
	v_cvt_pk_f32_fp8_sdwa v[220:221], v113 src0_sel:WORD_1
	v_pk_fma_f32 v[202:203], v[178:179], v[218:219], v[202:203] op_sel_hi:[0,1,1]
	v_pk_fma_f32 v[204:205], v[178:179], v[220:221], v[204:205] op_sel_hi:[0,1,1]
	v_cvt_pk_f32_fp8_e32 v[214:215], v114
	v_cvt_pk_f32_fp8_sdwa v[216:217], v114 src0_sel:WORD_1
	v_pk_fma_f32 v[206:207], v[178:179], v[214:215], v[206:207] op_sel_hi:[0,1,1]
	v_pk_fma_f32 v[208:209], v[178:179], v[216:217], v[208:209] op_sel_hi:[0,1,1]
	v_cvt_pk_f32_fp8_e32 v[218:219], v115
	v_cvt_pk_f32_fp8_sdwa v[220:221], v115 src0_sel:WORD_1
	v_pk_fma_f32 v[210:211], v[178:179], v[218:219], v[210:211] op_sel_hi:[0,1,1]
	v_pk_fma_f32 v[212:213], v[178:179], v[220:221], v[212:213] op_sel_hi:[0,1,1]
	s_waitcnt vmcnt(26)
	v_cvt_pk_f32_fp8_e32 v[214:215], v116
	v_cvt_pk_f32_fp8_sdwa v[216:217], v116 src0_sel:WORD_1
	v_pk_fma_f32 v[198:199], v[178:179], v[214:215], v[198:199] op_sel:[1,0,0]
	v_pk_fma_f32 v[200:201], v[178:179], v[216:217], v[200:201] op_sel:[1,0,0]
	v_cvt_pk_f32_fp8_e32 v[218:219], v117
	v_cvt_pk_f32_fp8_sdwa v[220:221], v117 src0_sel:WORD_1
	v_pk_fma_f32 v[202:203], v[178:179], v[218:219], v[202:203] op_sel:[1,0,0]
	v_pk_fma_f32 v[204:205], v[178:179], v[220:221], v[204:205] op_sel:[1,0,0]
	v_cvt_pk_f32_fp8_e32 v[214:215], v118
	v_cvt_pk_f32_fp8_sdwa v[216:217], v118 src0_sel:WORD_1
	v_pk_fma_f32 v[206:207], v[178:179], v[214:215], v[206:207] op_sel:[1,0,0]
	v_pk_fma_f32 v[208:209], v[178:179], v[216:217], v[208:209] op_sel:[1,0,0]
	v_cvt_pk_f32_fp8_e32 v[218:219], v119
	v_cvt_pk_f32_fp8_sdwa v[220:221], v119 src0_sel:WORD_1
	v_pk_fma_f32 v[210:211], v[178:179], v[218:219], v[210:211] op_sel:[1,0,0]
	v_pk_fma_f32 v[212:213], v[178:179], v[220:221], v[212:213] op_sel:[1,0,0]
	s_waitcnt lgkmcnt(0)
	v_lshl_add_u32 v174, v174, 8, v138
	v_lshl_add_u32 v175, v175, 8, v138
	v_lshl_add_u32 v176, v176, 8, v138
	v_lshl_add_u32 v177, v177, 8, v138
	buffer_load_dwordx4 v[96:99], v174, s[16:19], s26 offen
	buffer_load_dwordx4 v[100:103], v175, s[16:19], s26 offen
	buffer_load_dwordx4 v[104:107], v176, s[16:19], s26 offen
	buffer_load_dwordx4 v[108:111], v177, s[16:19], s26 offen
	s_waitcnt vmcnt(29)
	v_cvt_pk_f32_fp8_e32 v[214:215], v120
	v_cvt_pk_f32_fp8_sdwa v[216:217], v120 src0_sel:WORD_1
	v_pk_fma_f32 v[198:199], v[180:181], v[214:215], v[198:199] op_sel_hi:[0,1,1]
	v_pk_fma_f32 v[200:201], v[180:181], v[216:217], v[200:201] op_sel_hi:[0,1,1]
	v_cvt_pk_f32_fp8_e32 v[218:219], v121
	v_cvt_pk_f32_fp8_sdwa v[220:221], v121 src0_sel:WORD_1
	v_pk_fma_f32 v[202:203], v[180:181], v[218:219], v[202:203] op_sel_hi:[0,1,1]
	v_pk_fma_f32 v[204:205], v[180:181], v[220:221], v[204:205] op_sel_hi:[0,1,1]
	v_cvt_pk_f32_fp8_e32 v[214:215], v122
	v_cvt_pk_f32_fp8_sdwa v[216:217], v122 src0_sel:WORD_1
	v_pk_fma_f32 v[206:207], v[180:181], v[214:215], v[206:207] op_sel_hi:[0,1,1]
	v_pk_fma_f32 v[208:209], v[180:181], v[216:217], v[208:209] op_sel_hi:[0,1,1]
	v_cvt_pk_f32_fp8_e32 v[218:219], v123
	v_cvt_pk_f32_fp8_sdwa v[220:221], v123 src0_sel:WORD_1
	v_pk_fma_f32 v[210:211], v[180:181], v[218:219], v[210:211] op_sel_hi:[0,1,1]
	v_pk_fma_f32 v[212:213], v[180:181], v[220:221], v[212:213] op_sel_hi:[0,1,1]
	s_waitcnt vmcnt(28)
; __device__ __forceinline__ unsigned cvt_pk_bf16(float lo, float hi) { unsigned r; asm volatile("v_cvt_pk_bf16_f32 %0, %1, %2" : "=v"(r) : "v"(lo), "v"(hi)); return r; }
; #define LAS __attribute__((address_space(3)))
; #define LDS_WAIT() asm volatile("s_waitcnt lgkmcnt(0)" ::: "memory")
; __device__ __forceinline__ void kv8_pv(const u32x4 (&buf)[8], f32x2v (&o2)[8], const LAS float* srow, int b) {
;     const LAS f32x4* p4 = (const LAS f32x4*)(srow + b * 8);
;     const f32x4 p0 = p4[0], p1 = p4[1];
;     const float p[8] = {p0.x, p0.y, p0.z, p0.w, p1.x, p1.y, p1.z, p1.w};
; #pragma unroll
;     for (int u = 0; u < 8; ++u) {
;         const u32x4 v = buf[u]; const f32x2v pp = {p[u], p[u]};
;         o2[0] = __builtin_elementwise_fma(pp, __builtin_amdgcn_cvt_pk_f32_fp8(v.x, false), o2[0]); o2[1] = __builtin_elementwise_fma(pp, __builtin_amdgcn_cvt_pk_f32_fp8(v.x, true), o2[1]);
;         o2[2] = __builtin_elementwise_fma(pp, __builtin_amdgcn_cvt_pk_f32_fp8(v.y, false), o2[2]); o2[3] = __builtin_elementwise_fma(pp, __builtin_amdgcn_cvt_pk_f32_fp8(v.y, true), o2[3]);
;         o2[4] = __builtin_elementwise_fma(pp, __builtin_amdgcn_cvt_pk_f32_fp8(v.z, false), o2[4]); o2[5] = __builtin_elementwise_fma(pp, __builtin_amdgcn_cvt_pk_f32_fp8(v.z, true), o2[5]);
;         o2[6] = __builtin_elementwise_fma(pp, __builtin_amdgcn_cvt_pk_f32_fp8(v.w, false), o2[6]); o2[7] = __builtin_elementwise_fma(pp, __builtin_amdgcn_cvt_pk_f32_fp8(v.w, true), o2[7]);
;     }
; }
; __device__ __forceinline__ void attn_query8(const unsigned char* __restrict__ KV8, const bf16_t* __restrict__ Z, const int* __restrict__ SEL, bf16_t* __restrict__ YMIX, int t, LAS float* sbuf  ) {
;     ...
;     u32x4 o0, o1;
;     o0.x = cvt_pk_bf16(o[0].x, o[0].y); o0.y = cvt_pk_bf16(o[1].x, o[1].y); o0.z = cvt_pk_bf16(o[2].x, o[2].y); o0.w = cvt_pk_bf16(o[3].x, o[3].y);
;     o1.x = cvt_pk_bf16(o[4].x, o[4].y); o1.y = cvt_pk_bf16(o[5].x, o[5].y); o1.z = cvt_pk_bf16(o[6].x, o[6].y); o1.w = cvt_pk_bf16(o[7].x, o[7].y);
;     u32x4* yp = (u32x4*)(YMIX + (size_t)t * D_ + 1024 + lane * 16);
;     yp[0] = o0; yp[1] = o1;
;     LDS_WAIT();
	v_cvt_pk_f32_fp8_e32 v[214:215], v124
	v_cvt_pk_f32_fp8_sdwa v[216:217], v124 src0_sel:WORD_1
	v_pk_fma_f32 v[198:199], v[180:181], v[214:215], v[198:199] op_sel:[1,0,0]
	v_pk_fma_f32 v[200:201], v[180:181], v[216:217], v[200:201] op_sel:[1,0,0]
	v_cvt_pk_f32_fp8_e32 v[218:219], v125
	v_cvt_pk_f32_fp8_sdwa v[220:221], v125 src0_sel:WORD_1
	v_pk_fma_f32 v[202:203], v[180:181], v[218:219], v[202:203] op_sel:[1,0,0]
	v_pk_fma_f32 v[204:205], v[180:181], v[220:221], v[204:205] op_sel:[1,0,0]
	v_cvt_pk_f32_fp8_e32 v[214:215], v126
	v_cvt_pk_f32_fp8_sdwa v[216:217], v126 src0_sel:WORD_1
	v_pk_fma_f32 v[206:207], v[180:181], v[214:215], v[206:207] op_sel:[1,0,0]
	v_pk_fma_f32 v[208:209], v[180:181], v[216:217], v[208:209] op_sel:[1,0,0]
	v_cvt_pk_f32_fp8_e32 v[218:219], v127
	v_cvt_pk_f32_fp8_sdwa v[220:221], v127 src0_sel:WORD_1
	v_pk_fma_f32 v[210:211], v[180:181], v[218:219], v[210:211] op_sel:[1,0,0]
	v_pk_fma_f32 v[212:213], v[180:181], v[220:221], v[212:213] op_sel:[1,0,0]
	ds_read_b128 v[178:181], v139 offset:112
	v_add_f32_dpp v198, v198, v198 row_ror:8 row_mask:0xf bank_mask:0x3
	v_add_f32_dpp v199, v199, v199 row_ror:8 row_mask:0xf bank_mask:0x3
	v_add_f32_dpp v200, v200, v200 row_ror:8 row_mask:0xf bank_mask:0x3
	v_add_f32_dpp v201, v201, v201 row_ror:8 row_mask:0xf bank_mask:0x3
	v_add_f32_dpp v202, v202, v202 row_ror:8 row_mask:0xf bank_mask:0x3
	v_add_f32_dpp v203, v203, v203 row_ror:8 row_mask:0xf bank_mask:0x3
	v_add_f32_dpp v204, v204, v204 row_ror:8 row_mask:0xf bank_mask:0x3
	v_add_f32_dpp v205, v205, v205 row_ror:8 row_mask:0xf bank_mask:0x3
	v_add_f32_dpp v206, v206, v206 row_ror:8 row_mask:0xf bank_mask:0xc
	v_add_f32_dpp v207, v207, v207 row_ror:8 row_mask:0xf bank_mask:0xc
	v_add_f32_dpp v208, v208, v208 row_ror:8 row_mask:0xf bank_mask:0xc
	v_add_f32_dpp v209, v209, v209 row_ror:8 row_mask:0xf bank_mask:0xc
	v_add_f32_dpp v210, v210, v210 row_ror:8 row_mask:0xf bank_mask:0xc
	v_add_f32_dpp v211, v211, v211 row_ror:8 row_mask:0xf bank_mask:0xc
	v_add_f32_dpp v212, v212, v212 row_ror:8 row_mask:0xf bank_mask:0xc
	v_add_f32_dpp v213, v213, v213 row_ror:8 row_mask:0xf bank_mask:0xc
	v_mov_b32_dpp v198, v206 quad_perm:[0,1,2,3] row_mask:0xf bank_mask:0xc
	v_mov_b32_dpp v199, v207 quad_perm:[0,1,2,3] row_mask:0xf bank_mask:0xc
	v_mov_b32_dpp v200, v208 quad_perm:[0,1,2,3] row_mask:0xf bank_mask:0xc
	v_mov_b32_dpp v201, v209 quad_perm:[0,1,2,3] row_mask:0xf bank_mask:0xc
	v_mov_b32_dpp v202, v210 quad_perm:[0,1,2,3] row_mask:0xf bank_mask:0xc
	v_mov_b32_dpp v203, v211 quad_perm:[0,1,2,3] row_mask:0xf bank_mask:0xc
	v_mov_b32_dpp v204, v212 quad_perm:[0,1,2,3] row_mask:0xf bank_mask:0xc
	v_mov_b32_dpp v205, v213 quad_perm:[0,1,2,3] row_mask:0xf bank_mask:0xc
	s_waitcnt lgkmcnt(0)
	v_lshl_add_u32 v178, v178, 8, v138
	v_lshl_add_u32 v179, v179, 8, v138
	v_lshl_add_u32 v180, v180, 8, v138
	v_lshl_add_u32 v181, v181, 8, v138
	buffer_load_dwordx4 v[112:115], v178, s[16:19], s26 offen
	buffer_load_dwordx4 v[116:119], v179, s[16:19], s26 offen
	buffer_load_dwordx4 v[120:123], v180, s[16:19], s26 offen
	buffer_load_dwordx4 v[124:127], v181, s[16:19], s26 offen
	ds_bpermute_b32 v214, v140, v198
	ds_bpermute_b32 v215, v140, v199
	ds_bpermute_b32 v216, v140, v200
	ds_bpermute_b32 v217, v140, v201
	ds_bpermute_b32 v218, v140, v202
	ds_bpermute_b32 v219, v140, v203
	ds_bpermute_b32 v220, v140, v204
	ds_bpermute_b32 v221, v140, v205
	s_waitcnt lgkmcnt(0)
	v_add_f32_e32 v198, v198, v214
	v_add_f32_e32 v199, v199, v215
	v_add_f32_e32 v200, v200, v216
	v_add_f32_e32 v201, v201, v217
	v_add_f32_e32 v202, v202, v218
	v_add_f32_e32 v203, v203, v219
	v_add_f32_e32 v204, v204, v220
	v_add_f32_e32 v205, v205, v221
	ds_bpermute_b32 v214, v141, v198
	ds_bpermute_b32 v215, v141, v199
	ds_bpermute_b32 v216, v141, v200
	ds_bpermute_b32 v217, v141, v201
	ds_bpermute_b32 v218, v141, v202
	ds_bpermute_b32 v219, v141, v203
	ds_bpermute_b32 v220, v141, v204
	ds_bpermute_b32 v221, v141, v205
	s_waitcnt lgkmcnt(0)
	v_add_f32_e32 v198, v198, v214
	v_add_f32_e32 v199, v199, v215
	v_add_f32_e32 v200, v200, v216
	v_add_f32_e32 v201, v201, v217
	v_add_f32_e32 v202, v202, v218
	v_add_f32_e32 v203, v203, v219
	v_add_f32_e32 v204, v204, v220
	v_add_f32_e32 v205, v205, v221
	s_ashr_i32 s81, s80, 31
	s_lshl_b64 s[10:11], s[80:81], 12
	s_add_u32 s10, s14, s10
	s_addc_u32 s11, s15, s11
	v_mul_f32_e32 v198, v198, v149
	v_mul_f32_e32 v199, v199, v149
	v_mul_f32_e32 v200, v200, v149
	v_mul_f32_e32 v201, v201, v149
	v_mul_f32_e32 v202, v202, v149
	v_mul_f32_e32 v203, v203, v149
	v_mul_f32_e32 v204, v204, v149
	v_mul_f32_e32 v205, v205, v149
	v_cvt_pk_bf16_f32 v214, v198, v199
	v_cvt_pk_bf16_f32 v215, v200, v201
	v_cvt_pk_bf16_f32 v216, v202, v203
	v_cvt_pk_bf16_f32 v217, v204, v205
	v_cmp_gt_u32_e32 vcc, 16, v144
	s_and_saveexec_b64 s[12:13], vcc
	global_store_dwordx4 v238, v[214:217], s[10:11] offset:2048
	s_mov_b64 exec, s[12:13]
	s_addk_i32 s80, 0x100
	s_cmpk_gt_i32 s80, 0x3fff
	s_cbranch_scc0 .Latt_unit
	s_waitcnt vmcnt(0)
